# write-through (sc1) stores in the three one-tile-per-workgroup residual epilogues (out-proj x2, dense down): nothing of theirs left dirty in L2 at the following seam
# baseline (speedup 1.0000x reference)
;     __device__ __forceinline__ void operator()(const f32x4 (&acc)[2][2][4][2], const Unit& u, int wr, int wc, int fr, int fq) const {
;         int row0 = u.pm * BM + wr * 64 + fr, col0 = u.pn * BM + wc * 32 + 4 * fq; asm volatile("" : "+v"(row0), "+v"(col0));
;         typedef float f32x2v __attribute__((ext_vector_type(2)));
; #pragma unroll
;         for (int ai = 0; ai < 2; ++ai)
; #pragma unroll
;             for (int m = 0; m < 4; ++m) { const int row = row0 + ai * HALF + m * 16; const size_t ro = (size_t)row * 1024 + col0; const f32x2v st = *(const f32x2v*)(p.stats + 2 * row);
; #pragma unroll
;                 for (int bj = 0; bj < 2; ++bj)
; #pragma unroll
;                     for (int n = 0; n < 2; ++n) { const int c = col0 + bj * HALF + n * 16; const size_t off = ro + bj * HALF + n * 16;
;                         const f32x4 sv = *(const f32x4*)(p.src + off), gv = *(const f32x4*)(p.g + c), bv = *(const f32x4*)(p.b + c);
;                         const f32x4 hv = (sv - st.x) * st.y * gv + bv; *(f32x4*)(z + off) = hv * alpha + acc[ai][bj][m][n] * sc; }
;                 asm volatile("" ::: "memory"); }
.LBB0_781:
	s_lshl_b32 s18, s64, 8
	v_mbcnt_lo_u32_b32 v132, -1, 0
	v_mbcnt_hi_u32_b32 v132, -1, v132
	s_add_i32 s18, s18, s71
	v_and_or_b32 v138, v132, 15, s18
	s_lshl_b32 s18, s63, 8
	v_lshrrev_b32_e32 v132, 2, v132
	v_and_or_b32 v132, v132, 12, s18
	v_or_b32_e32 v136, s75, v132
	s_andn2_b64 vcc, exec, s[4:5]
	v_lshlrev_b32_e32 v244, 12, v138
	v_lshlrev_b32_e32 v246, 3, v138
	v_lshlrev_b32_e32 v247, 2, v136
	v_lshl_add_u32 v244, v136, 2, v244
	global_load_dwordx2 v[180:181], v246, s[26:27]
	global_load_dwordx2 v[182:183], v246, s[26:27] offset:128
	global_load_dwordx2 v[184:185], v246, s[26:27] offset:256
	global_load_dwordx2 v[186:187], v246, s[26:27] offset:384
	global_load_dwordx2 v[188:189], v246, s[26:27] offset:1024
	global_load_dwordx2 v[190:191], v246, s[26:27] offset:1152
	global_load_dwordx2 v[192:193], v246, s[26:27] offset:1280
	global_load_dwordx2 v[194:195], v246, s[26:27] offset:1408
	v_mov_b32_e32 v245, v244
	global_load_dwordx4 v[148:151], v247, s[20:21]
	global_load_dwordx4 v[152:155], v247, s[20:21] offset:64
	global_load_dwordx4 v[156:159], v247, s[20:21] offset:512
	global_load_dwordx4 v[160:163], v247, s[20:21] offset:576
	global_load_dwordx4 v[164:167], v247, s[22:23]
	global_load_dwordx4 v[168:171], v247, s[22:23] offset:64
	global_load_dwordx4 v[172:175], v247, s[22:23] offset:512
	global_load_dwordx4 v[176:179], v247, s[22:23] offset:576
	s_mov_b64 s[4:5], -1
	global_load_dwordx4 v[196:199], v244, s[10:11]
	global_load_dwordx4 v[200:203], v244, s[10:11] offset:64
	global_load_dwordx4 v[204:207], v244, s[10:11] offset:512
	global_load_dwordx4 v[208:211], v244, s[10:11] offset:576
	v_add_u32_e32 v244, 0x10000, v244
	global_load_dwordx4 v[212:215], v244, s[10:11]
	global_load_dwordx4 v[216:219], v244, s[10:11] offset:64
	global_load_dwordx4 v[220:223], v244, s[10:11] offset:512
	global_load_dwordx4 v[224:227], v244, s[10:11] offset:576
	v_add_u32_e32 v244, 0x10000, v244
	global_load_dwordx4 v[228:231], v244, s[10:11]
	global_load_dwordx4 v[232:235], v244, s[10:11] offset:64
	global_load_dwordx4 v[236:239], v244, s[10:11] offset:512
	global_load_dwordx4 v[240:243], v244, s[10:11] offset:576
	v_add_u32_e32 v244, 0x10000, v244
	s_waitcnt vmcnt(8)
	v_sub_f32_e32 v197, v197, v180
	v_sub_f32_e32 v196, v196, v180
	v_sub_f32_e32 v199, v199, v180
	v_sub_f32_e32 v198, v198, v180
	v_pk_mul_f32 v[198:199], v[180:181], v[198:199] op_sel:[1,0]
	v_pk_mul_f32 v[196:197], v[180:181], v[196:197] op_sel:[1,0]
	v_pk_fma_f32 v[198:199], v[150:151], v[198:199], v[166:167]
	v_pk_fma_f32 v[196:197], v[148:149], v[196:197], v[164:165]
	v_pk_fma_f32 v[126:127], v[198:199], s[46:47], v[126:127] op_sel_hi:[1,0,1]
	v_pk_fma_f32 v[124:125], v[196:197], s[46:47], v[124:125] op_sel_hi:[1,0,1]
	v_sub_f32_e32 v201, v201, v180
	v_sub_f32_e32 v200, v200, v180
	v_sub_f32_e32 v203, v203, v180
	v_sub_f32_e32 v202, v202, v180
	v_pk_mul_f32 v[202:203], v[180:181], v[202:203] op_sel:[1,0]
	v_pk_mul_f32 v[200:201], v[180:181], v[200:201] op_sel:[1,0]
	v_pk_fma_f32 v[202:203], v[154:155], v[202:203], v[170:171]
	v_pk_fma_f32 v[200:201], v[152:153], v[200:201], v[168:169]
	v_pk_fma_f32 v[122:123], v[202:203], s[46:47], v[122:123] op_sel_hi:[1,0,1]
	v_pk_fma_f32 v[120:121], v[200:201], s[46:47], v[120:121] op_sel_hi:[1,0,1]
	v_sub_f32_e32 v205, v205, v180
	v_sub_f32_e32 v204, v204, v180
	v_sub_f32_e32 v207, v207, v180
	v_sub_f32_e32 v206, v206, v180
	v_pk_mul_f32 v[206:207], v[180:181], v[206:207] op_sel:[1,0]
	v_pk_mul_f32 v[204:205], v[180:181], v[204:205] op_sel:[1,0]
	v_pk_fma_f32 v[206:207], v[158:159], v[206:207], v[174:175]
	v_pk_fma_f32 v[204:205], v[156:157], v[204:205], v[172:173]
	v_pk_fma_f32 v[118:119], v[206:207], s[46:47], v[118:119] op_sel_hi:[1,0,1]
	v_pk_fma_f32 v[116:117], v[204:205], s[46:47], v[116:117] op_sel_hi:[1,0,1]
	v_sub_f32_e32 v209, v209, v180
	v_sub_f32_e32 v208, v208, v180
	v_sub_f32_e32 v211, v211, v180
	v_sub_f32_e32 v210, v210, v180
	v_pk_mul_f32 v[210:211], v[180:181], v[210:211] op_sel:[1,0]
	v_pk_mul_f32 v[208:209], v[180:181], v[208:209] op_sel:[1,0]
	v_pk_fma_f32 v[210:211], v[162:163], v[210:211], v[178:179]
	v_pk_fma_f32 v[208:209], v[160:161], v[208:209], v[176:177]
	v_pk_fma_f32 v[114:115], v[210:211], s[46:47], v[114:115] op_sel_hi:[1,0,1]
	v_pk_fma_f32 v[112:113], v[208:209], s[46:47], v[112:113] op_sel_hi:[1,0,1]
	global_store_dwordx4 v245, v[124:127], s[28:29] sc1
	global_store_dwordx4 v245, v[120:123], s[28:29] offset:64 sc1
	global_store_dwordx4 v245, v[116:119], s[28:29] offset:512 sc1
	global_store_dwordx4 v245, v[112:115], s[28:29] offset:576 sc1
	v_add_u32_e32 v245, 0x10000, v245
	global_load_dwordx4 v[196:199], v244, s[10:11]
	global_load_dwordx4 v[200:203], v244, s[10:11] offset:64
	global_load_dwordx4 v[204:207], v244, s[10:11] offset:512
	global_load_dwordx4 v[208:211], v244, s[10:11] offset:576
	v_add_u32_e32 v244, 0x50000, v244
	s_waitcnt vmcnt(12)
;     __device__ __forceinline__ void operator()(const f32x4 (&acc)[2][2][4][2], const Unit& u, int wr, int wc, int fr, int fq) const {
;     ...
;             for (int m = 0; m < 4; ++m) { const int row = row0 + ai * HALF + m * 16; const size_t ro = (size_t)row * 1024 + col0; const f32x2v st = *(const f32x2v*)(p.stats + 2 * row);
; #pragma unroll
;                 for (int bj = 0; bj < 2; ++bj)
; #pragma unroll
;                     for (int n = 0; n < 2; ++n) { const int c = col0 + bj * HALF + n * 16; const size_t off = ro + bj * HALF + n * 16;
;                         const f32x4 sv = *(const f32x4*)(p.src + off), gv = *(const f32x4*)(p.g + c), bv = *(const f32x4*)(p.b + c);
;                         const f32x4 hv = (sv - st.x) * st.y * gv + bv; *(f32x4*)(z + off) = hv * alpha + acc[ai][bj][m][n] * sc; }
;                 asm volatile("" ::: "memory"); }
	v_sub_f32_e32 v213, v213, v182
	v_sub_f32_e32 v212, v212, v182
	v_sub_f32_e32 v215, v215, v182
	v_sub_f32_e32 v214, v214, v182
	v_pk_mul_f32 v[214:215], v[182:183], v[214:215] op_sel:[1,0]
	v_pk_mul_f32 v[212:213], v[182:183], v[212:213] op_sel:[1,0]
	v_pk_fma_f32 v[214:215], v[150:151], v[214:215], v[166:167]
	v_pk_fma_f32 v[212:213], v[148:149], v[212:213], v[164:165]
	v_pk_fma_f32 v[110:111], v[214:215], s[46:47], v[110:111] op_sel_hi:[1,0,1]
	v_pk_fma_f32 v[108:109], v[212:213], s[46:47], v[108:109] op_sel_hi:[1,0,1]
	v_sub_f32_e32 v217, v217, v182
	v_sub_f32_e32 v216, v216, v182
	v_sub_f32_e32 v219, v219, v182
	v_sub_f32_e32 v218, v218, v182
	v_pk_mul_f32 v[218:219], v[182:183], v[218:219] op_sel:[1,0]
	v_pk_mul_f32 v[216:217], v[182:183], v[216:217] op_sel:[1,0]
	v_pk_fma_f32 v[218:219], v[154:155], v[218:219], v[170:171]
	v_pk_fma_f32 v[216:217], v[152:153], v[216:217], v[168:169]
	v_pk_fma_f32 v[106:107], v[218:219], s[46:47], v[106:107] op_sel_hi:[1,0,1]
	v_pk_fma_f32 v[104:105], v[216:217], s[46:47], v[104:105] op_sel_hi:[1,0,1]
	v_sub_f32_e32 v221, v221, v182
	v_sub_f32_e32 v220, v220, v182
	v_sub_f32_e32 v223, v223, v182
	v_sub_f32_e32 v222, v222, v182
	v_pk_mul_f32 v[222:223], v[182:183], v[222:223] op_sel:[1,0]
	v_pk_mul_f32 v[220:221], v[182:183], v[220:221] op_sel:[1,0]
	v_pk_fma_f32 v[222:223], v[158:159], v[222:223], v[174:175]
	v_pk_fma_f32 v[220:221], v[156:157], v[220:221], v[172:173]
	v_pk_fma_f32 v[102:103], v[222:223], s[46:47], v[102:103] op_sel_hi:[1,0,1]
	v_pk_fma_f32 v[100:101], v[220:221], s[46:47], v[100:101] op_sel_hi:[1,0,1]
	v_sub_f32_e32 v225, v225, v182
	v_sub_f32_e32 v224, v224, v182
	v_sub_f32_e32 v227, v227, v182
	v_sub_f32_e32 v226, v226, v182
	v_pk_mul_f32 v[226:227], v[182:183], v[226:227] op_sel:[1,0]
	v_pk_mul_f32 v[224:225], v[182:183], v[224:225] op_sel:[1,0]
	v_pk_fma_f32 v[226:227], v[162:163], v[226:227], v[178:179]
	v_pk_fma_f32 v[224:225], v[160:161], v[224:225], v[176:177]
	v_pk_fma_f32 v[98:99], v[226:227], s[46:47], v[98:99] op_sel_hi:[1,0,1]
	v_pk_fma_f32 v[96:97], v[224:225], s[46:47], v[96:97] op_sel_hi:[1,0,1]
	global_store_dwordx4 v245, v[108:111], s[28:29] sc1
	global_store_dwordx4 v245, v[104:107], s[28:29] offset:64 sc1
	global_store_dwordx4 v245, v[100:103], s[28:29] offset:512 sc1
	global_store_dwordx4 v245, v[96:99], s[28:29] offset:576 sc1
	v_add_u32_e32 v245, 0x10000, v245
	global_load_dwordx4 v[212:215], v244, s[10:11]
	global_load_dwordx4 v[216:219], v244, s[10:11] offset:64
	global_load_dwordx4 v[220:223], v244, s[10:11] offset:512
	global_load_dwordx4 v[224:227], v244, s[10:11] offset:576
	v_add_u32_e32 v244, 0x10000, v244
	s_waitcnt vmcnt(16)
	v_sub_f32_e32 v229, v229, v184
	v_sub_f32_e32 v228, v228, v184
	v_sub_f32_e32 v231, v231, v184
	v_sub_f32_e32 v230, v230, v184
	v_pk_mul_f32 v[230:231], v[184:185], v[230:231] op_sel:[1,0]
	v_pk_mul_f32 v[228:229], v[184:185], v[228:229] op_sel:[1,0]
	v_pk_fma_f32 v[230:231], v[150:151], v[230:231], v[166:167]
	v_pk_fma_f32 v[228:229], v[148:149], v[228:229], v[164:165]
	v_pk_fma_f32 v[94:95], v[230:231], s[46:47], v[94:95] op_sel_hi:[1,0,1]
	v_pk_fma_f32 v[92:93], v[228:229], s[46:47], v[92:93] op_sel_hi:[1,0,1]
	v_sub_f32_e32 v233, v233, v184
	v_sub_f32_e32 v232, v232, v184
	v_sub_f32_e32 v235, v235, v184
	v_sub_f32_e32 v234, v234, v184
	v_pk_mul_f32 v[234:235], v[184:185], v[234:235] op_sel:[1,0]
	v_pk_mul_f32 v[232:233], v[184:185], v[232:233] op_sel:[1,0]
	v_pk_fma_f32 v[234:235], v[154:155], v[234:235], v[170:171]
	v_pk_fma_f32 v[232:233], v[152:153], v[232:233], v[168:169]
	v_pk_fma_f32 v[90:91], v[234:235], s[46:47], v[90:91] op_sel_hi:[1,0,1]
	v_pk_fma_f32 v[88:89], v[232:233], s[46:47], v[88:89] op_sel_hi:[1,0,1]
	v_sub_f32_e32 v237, v237, v184
	v_sub_f32_e32 v236, v236, v184
	v_sub_f32_e32 v239, v239, v184
	v_sub_f32_e32 v238, v238, v184
	v_pk_mul_f32 v[238:239], v[184:185], v[238:239] op_sel:[1,0]
	v_pk_mul_f32 v[236:237], v[184:185], v[236:237] op_sel:[1,0]
	v_pk_fma_f32 v[238:239], v[158:159], v[238:239], v[174:175]
	v_pk_fma_f32 v[236:237], v[156:157], v[236:237], v[172:173]
	v_pk_fma_f32 v[86:87], v[238:239], s[46:47], v[86:87] op_sel_hi:[1,0,1]
	v_pk_fma_f32 v[84:85], v[236:237], s[46:47], v[84:85] op_sel_hi:[1,0,1]
	v_sub_f32_e32 v241, v241, v184
	v_sub_f32_e32 v240, v240, v184
	v_sub_f32_e32 v243, v243, v184
	v_sub_f32_e32 v242, v242, v184
	v_pk_mul_f32 v[242:243], v[184:185], v[242:243] op_sel:[1,0]
	v_pk_mul_f32 v[240:241], v[184:185], v[240:241] op_sel:[1,0]
	v_pk_fma_f32 v[242:243], v[162:163], v[242:243], v[178:179]
	v_pk_fma_f32 v[240:241], v[160:161], v[240:241], v[176:177]
	v_pk_fma_f32 v[82:83], v[242:243], s[46:47], v[82:83] op_sel_hi:[1,0,1]
	v_pk_fma_f32 v[80:81], v[240:241], s[46:47], v[80:81] op_sel_hi:[1,0,1]
	global_store_dwordx4 v245, v[92:95], s[28:29] sc1
	global_store_dwordx4 v245, v[88:91], s[28:29] offset:64 sc1
	global_store_dwordx4 v245, v[84:87], s[28:29] offset:512 sc1
	global_store_dwordx4 v245, v[80:83], s[28:29] offset:576 sc1
	v_add_u32_e32 v245, 0x10000, v245
	global_load_dwordx4 v[228:231], v244, s[10:11]
	global_load_dwordx4 v[232:235], v244, s[10:11] offset:64
	global_load_dwordx4 v[236:239], v244, s[10:11] offset:512
	global_load_dwordx4 v[240:243], v244, s[10:11] offset:576
	v_add_u32_e32 v244, 0x10000, v244
	s_waitcnt vmcnt(16)
;     __device__ __forceinline__ void operator()(const f32x4 (&acc)[2][2][4][2], const Unit& u, int wr, int wc, int fr, int fq) const {
;     ...
;             for (int m = 0; m < 4; ++m) { const int row = row0 + ai * HALF + m * 16; const size_t ro = (size_t)row * 1024 + col0; const f32x2v st = *(const f32x2v*)(p.stats + 2 * row);
; #pragma unroll
;                 for (int bj = 0; bj < 2; ++bj)
; #pragma unroll
;                     for (int n = 0; n < 2; ++n) { const int c = col0 + bj * HALF + n * 16; const size_t off = ro + bj * HALF + n * 16;
;                         const f32x4 sv = *(const f32x4*)(p.src + off), gv = *(const f32x4*)(p.g + c), bv = *(const f32x4*)(p.b + c);
;                         const f32x4 hv = (sv - st.x) * st.y * gv + bv; *(f32x4*)(z + off) = hv * alpha + acc[ai][bj][m][n] * sc; }
;                 asm volatile("" ::: "memory"); }
	v_sub_f32_e32 v197, v197, v186
	v_sub_f32_e32 v196, v196, v186
	v_sub_f32_e32 v199, v199, v186
	v_sub_f32_e32 v198, v198, v186
	v_pk_mul_f32 v[198:199], v[186:187], v[198:199] op_sel:[1,0]
	v_pk_mul_f32 v[196:197], v[186:187], v[196:197] op_sel:[1,0]
	v_pk_fma_f32 v[198:199], v[150:151], v[198:199], v[166:167]
	v_pk_fma_f32 v[196:197], v[148:149], v[196:197], v[164:165]
	v_pk_fma_f32 v[78:79], v[198:199], s[46:47], v[78:79] op_sel_hi:[1,0,1]
	v_pk_fma_f32 v[76:77], v[196:197], s[46:47], v[76:77] op_sel_hi:[1,0,1]
	v_sub_f32_e32 v201, v201, v186
	v_sub_f32_e32 v200, v200, v186
	v_sub_f32_e32 v203, v203, v186
	v_sub_f32_e32 v202, v202, v186
	v_pk_mul_f32 v[202:203], v[186:187], v[202:203] op_sel:[1,0]
	v_pk_mul_f32 v[200:201], v[186:187], v[200:201] op_sel:[1,0]
	v_pk_fma_f32 v[202:203], v[154:155], v[202:203], v[170:171]
	v_pk_fma_f32 v[200:201], v[152:153], v[200:201], v[168:169]
	v_pk_fma_f32 v[74:75], v[202:203], s[46:47], v[74:75] op_sel_hi:[1,0,1]
	v_pk_fma_f32 v[72:73], v[200:201], s[46:47], v[72:73] op_sel_hi:[1,0,1]
	v_sub_f32_e32 v205, v205, v186
	v_sub_f32_e32 v204, v204, v186
	v_sub_f32_e32 v207, v207, v186
	v_sub_f32_e32 v206, v206, v186
	v_pk_mul_f32 v[206:207], v[186:187], v[206:207] op_sel:[1,0]
	v_pk_mul_f32 v[204:205], v[186:187], v[204:205] op_sel:[1,0]
	v_pk_fma_f32 v[206:207], v[158:159], v[206:207], v[174:175]
	v_pk_fma_f32 v[204:205], v[156:157], v[204:205], v[172:173]
	v_pk_fma_f32 v[70:71], v[206:207], s[46:47], v[70:71] op_sel_hi:[1,0,1]
	v_pk_fma_f32 v[68:69], v[204:205], s[46:47], v[68:69] op_sel_hi:[1,0,1]
	v_sub_f32_e32 v209, v209, v186
	v_sub_f32_e32 v208, v208, v186
	v_sub_f32_e32 v211, v211, v186
	v_sub_f32_e32 v210, v210, v186
	v_pk_mul_f32 v[210:211], v[186:187], v[210:211] op_sel:[1,0]
	v_pk_mul_f32 v[208:209], v[186:187], v[208:209] op_sel:[1,0]
	v_pk_fma_f32 v[210:211], v[162:163], v[210:211], v[178:179]
	v_pk_fma_f32 v[208:209], v[160:161], v[208:209], v[176:177]
	v_pk_fma_f32 v[66:67], v[210:211], s[46:47], v[66:67] op_sel_hi:[1,0,1]
	v_pk_fma_f32 v[64:65], v[208:209], s[46:47], v[64:65] op_sel_hi:[1,0,1]
	global_store_dwordx4 v245, v[76:79], s[28:29] sc1
	global_store_dwordx4 v245, v[72:75], s[28:29] offset:64 sc1
	global_store_dwordx4 v245, v[68:71], s[28:29] offset:512 sc1
	global_store_dwordx4 v245, v[64:67], s[28:29] offset:576 sc1
	v_add_u32_e32 v245, 0x50000, v245
	global_load_dwordx4 v[196:199], v244, s[10:11]
	global_load_dwordx4 v[200:203], v244, s[10:11] offset:64
	global_load_dwordx4 v[204:207], v244, s[10:11] offset:512
	global_load_dwordx4 v[208:211], v244, s[10:11] offset:576
	v_add_u32_e32 v244, 0x10000, v244
	s_waitcnt vmcnt(16)
	v_sub_f32_e32 v213, v213, v188
	v_sub_f32_e32 v212, v212, v188
	v_sub_f32_e32 v215, v215, v188
	v_sub_f32_e32 v214, v214, v188
	v_pk_mul_f32 v[214:215], v[188:189], v[214:215] op_sel:[1,0]
	v_pk_mul_f32 v[212:213], v[188:189], v[212:213] op_sel:[1,0]
	v_pk_fma_f32 v[214:215], v[150:151], v[214:215], v[166:167]
	v_pk_fma_f32 v[212:213], v[148:149], v[212:213], v[164:165]
	v_pk_fma_f32 v[62:63], v[214:215], s[46:47], v[62:63] op_sel_hi:[1,0,1]
	v_pk_fma_f32 v[60:61], v[212:213], s[46:47], v[60:61] op_sel_hi:[1,0,1]
	v_sub_f32_e32 v217, v217, v188
	v_sub_f32_e32 v216, v216, v188
	v_sub_f32_e32 v219, v219, v188
	v_sub_f32_e32 v218, v218, v188
	v_pk_mul_f32 v[218:219], v[188:189], v[218:219] op_sel:[1,0]
	v_pk_mul_f32 v[216:217], v[188:189], v[216:217] op_sel:[1,0]
	v_pk_fma_f32 v[218:219], v[154:155], v[218:219], v[170:171]
	v_pk_fma_f32 v[216:217], v[152:153], v[216:217], v[168:169]
	v_pk_fma_f32 v[58:59], v[218:219], s[46:47], v[58:59] op_sel_hi:[1,0,1]
	v_pk_fma_f32 v[56:57], v[216:217], s[46:47], v[56:57] op_sel_hi:[1,0,1]
	v_sub_f32_e32 v221, v221, v188
	v_sub_f32_e32 v220, v220, v188
	v_sub_f32_e32 v223, v223, v188
	v_sub_f32_e32 v222, v222, v188
	v_pk_mul_f32 v[222:223], v[188:189], v[222:223] op_sel:[1,0]
	v_pk_mul_f32 v[220:221], v[188:189], v[220:221] op_sel:[1,0]
	v_pk_fma_f32 v[222:223], v[158:159], v[222:223], v[174:175]
	v_pk_fma_f32 v[220:221], v[156:157], v[220:221], v[172:173]
	v_pk_fma_f32 v[54:55], v[222:223], s[46:47], v[54:55] op_sel_hi:[1,0,1]
	v_pk_fma_f32 v[52:53], v[220:221], s[46:47], v[52:53] op_sel_hi:[1,0,1]
	v_sub_f32_e32 v225, v225, v188
	v_sub_f32_e32 v224, v224, v188
	v_sub_f32_e32 v227, v227, v188
	v_sub_f32_e32 v226, v226, v188
	v_pk_mul_f32 v[226:227], v[188:189], v[226:227] op_sel:[1,0]
	v_pk_mul_f32 v[224:225], v[188:189], v[224:225] op_sel:[1,0]
	v_pk_fma_f32 v[226:227], v[162:163], v[226:227], v[178:179]
	v_pk_fma_f32 v[224:225], v[160:161], v[224:225], v[176:177]
	v_pk_fma_f32 v[50:51], v[226:227], s[46:47], v[50:51] op_sel_hi:[1,0,1]
	v_pk_fma_f32 v[48:49], v[224:225], s[46:47], v[48:49] op_sel_hi:[1,0,1]
	global_store_dwordx4 v245, v[60:63], s[28:29] sc1
	global_store_dwordx4 v245, v[56:59], s[28:29] offset:64 sc1
	global_store_dwordx4 v245, v[52:55], s[28:29] offset:512 sc1
	global_store_dwordx4 v245, v[48:51], s[28:29] offset:576 sc1
	v_add_u32_e32 v245, 0x10000, v245
	global_load_dwordx4 v[212:215], v244, s[10:11]
	global_load_dwordx4 v[216:219], v244, s[10:11] offset:64
	global_load_dwordx4 v[220:223], v244, s[10:11] offset:512
	global_load_dwordx4 v[224:227], v244, s[10:11] offset:576
	s_waitcnt vmcnt(16)
;     __device__ __forceinline__ void operator()(const f32x4 (&acc)[2][2][4][2], const Unit& u, int wr, int wc, int fr, int fq) const {
;     ...
;             for (int m = 0; m < 4; ++m) { const int row = row0 + ai * HALF + m * 16; const size_t ro = (size_t)row * 1024 + col0; const f32x2v st = *(const f32x2v*)(p.stats + 2 * row);
; #pragma unroll
;                 for (int bj = 0; bj < 2; ++bj)
; #pragma unroll
;                     for (int n = 0; n < 2; ++n) { const int c = col0 + bj * HALF + n * 16; const size_t off = ro + bj * HALF + n * 16;
;                         const f32x4 sv = *(const f32x4*)(p.src + off), gv = *(const f32x4*)(p.g + c), bv = *(const f32x4*)(p.b + c);
;                         const f32x4 hv = (sv - st.x) * st.y * gv + bv; *(f32x4*)(z + off) = hv * alpha + acc[ai][bj][m][n] * sc; }
;                 asm volatile("" ::: "memory"); }
	v_sub_f32_e32 v229, v229, v190
	v_sub_f32_e32 v228, v228, v190
	v_sub_f32_e32 v231, v231, v190
	v_sub_f32_e32 v230, v230, v190
	v_pk_mul_f32 v[230:231], v[190:191], v[230:231] op_sel:[1,0]
	v_pk_mul_f32 v[228:229], v[190:191], v[228:229] op_sel:[1,0]
	v_pk_fma_f32 v[230:231], v[150:151], v[230:231], v[166:167]
	v_pk_fma_f32 v[228:229], v[148:149], v[228:229], v[164:165]
	v_pk_fma_f32 v[46:47], v[230:231], s[46:47], v[46:47] op_sel_hi:[1,0,1]
	v_pk_fma_f32 v[44:45], v[228:229], s[46:47], v[44:45] op_sel_hi:[1,0,1]
	v_sub_f32_e32 v233, v233, v190
	v_sub_f32_e32 v232, v232, v190
	v_sub_f32_e32 v235, v235, v190
	v_sub_f32_e32 v234, v234, v190
	v_pk_mul_f32 v[234:235], v[190:191], v[234:235] op_sel:[1,0]
	v_pk_mul_f32 v[232:233], v[190:191], v[232:233] op_sel:[1,0]
	v_pk_fma_f32 v[234:235], v[154:155], v[234:235], v[170:171]
	v_pk_fma_f32 v[232:233], v[152:153], v[232:233], v[168:169]
	v_pk_fma_f32 v[42:43], v[234:235], s[46:47], v[42:43] op_sel_hi:[1,0,1]
	v_pk_fma_f32 v[40:41], v[232:233], s[46:47], v[40:41] op_sel_hi:[1,0,1]
	v_sub_f32_e32 v237, v237, v190
	v_sub_f32_e32 v236, v236, v190
	v_sub_f32_e32 v239, v239, v190
	v_sub_f32_e32 v238, v238, v190
	v_pk_mul_f32 v[238:239], v[190:191], v[238:239] op_sel:[1,0]
	v_pk_mul_f32 v[236:237], v[190:191], v[236:237] op_sel:[1,0]
	v_pk_fma_f32 v[238:239], v[158:159], v[238:239], v[174:175]
	v_pk_fma_f32 v[236:237], v[156:157], v[236:237], v[172:173]
	v_pk_fma_f32 v[38:39], v[238:239], s[46:47], v[38:39] op_sel_hi:[1,0,1]
	v_pk_fma_f32 v[36:37], v[236:237], s[46:47], v[36:37] op_sel_hi:[1,0,1]
	v_sub_f32_e32 v241, v241, v190
	v_sub_f32_e32 v240, v240, v190
	v_sub_f32_e32 v243, v243, v190
	v_sub_f32_e32 v242, v242, v190
	v_pk_mul_f32 v[242:243], v[190:191], v[242:243] op_sel:[1,0]
	v_pk_mul_f32 v[240:241], v[190:191], v[240:241] op_sel:[1,0]
	v_pk_fma_f32 v[242:243], v[162:163], v[242:243], v[178:179]
	v_pk_fma_f32 v[240:241], v[160:161], v[240:241], v[176:177]
	v_pk_fma_f32 v[34:35], v[242:243], s[46:47], v[34:35] op_sel_hi:[1,0,1]
	v_pk_fma_f32 v[32:33], v[240:241], s[46:47], v[32:33] op_sel_hi:[1,0,1]
	global_store_dwordx4 v245, v[44:47], s[28:29] sc1
	global_store_dwordx4 v245, v[40:43], s[28:29] offset:64 sc1
	global_store_dwordx4 v245, v[36:39], s[28:29] offset:512 sc1
	global_store_dwordx4 v245, v[32:35], s[28:29] offset:576 sc1
	v_add_u32_e32 v245, 0x10000, v245
	s_waitcnt vmcnt(12)
	v_sub_f32_e32 v197, v197, v192
	v_sub_f32_e32 v196, v196, v192
	v_sub_f32_e32 v199, v199, v192
	v_sub_f32_e32 v198, v198, v192
	v_pk_mul_f32 v[198:199], v[192:193], v[198:199] op_sel:[1,0]
	v_pk_mul_f32 v[196:197], v[192:193], v[196:197] op_sel:[1,0]
	v_pk_fma_f32 v[198:199], v[150:151], v[198:199], v[166:167]
	v_pk_fma_f32 v[196:197], v[148:149], v[196:197], v[164:165]
	v_pk_fma_f32 v[30:31], v[198:199], s[46:47], v[30:31] op_sel_hi:[1,0,1]
	v_pk_fma_f32 v[28:29], v[196:197], s[46:47], v[28:29] op_sel_hi:[1,0,1]
	v_sub_f32_e32 v201, v201, v192
	v_sub_f32_e32 v200, v200, v192
	v_sub_f32_e32 v203, v203, v192
	v_sub_f32_e32 v202, v202, v192
	v_pk_mul_f32 v[202:203], v[192:193], v[202:203] op_sel:[1,0]
	v_pk_mul_f32 v[200:201], v[192:193], v[200:201] op_sel:[1,0]
	v_pk_fma_f32 v[202:203], v[154:155], v[202:203], v[170:171]
	v_pk_fma_f32 v[200:201], v[152:153], v[200:201], v[168:169]
	v_pk_fma_f32 v[26:27], v[202:203], s[46:47], v[26:27] op_sel_hi:[1,0,1]
	v_pk_fma_f32 v[24:25], v[200:201], s[46:47], v[24:25] op_sel_hi:[1,0,1]
	v_sub_f32_e32 v205, v205, v192
	v_sub_f32_e32 v204, v204, v192
	v_sub_f32_e32 v207, v207, v192
	v_sub_f32_e32 v206, v206, v192
	v_pk_mul_f32 v[206:207], v[192:193], v[206:207] op_sel:[1,0]
	v_pk_mul_f32 v[204:205], v[192:193], v[204:205] op_sel:[1,0]
	v_pk_fma_f32 v[206:207], v[158:159], v[206:207], v[174:175]
	v_pk_fma_f32 v[204:205], v[156:157], v[204:205], v[172:173]
	v_pk_fma_f32 v[22:23], v[206:207], s[46:47], v[22:23] op_sel_hi:[1,0,1]
	v_pk_fma_f32 v[20:21], v[204:205], s[46:47], v[20:21] op_sel_hi:[1,0,1]
	v_sub_f32_e32 v209, v209, v192
	v_sub_f32_e32 v208, v208, v192
	v_sub_f32_e32 v211, v211, v192
	v_sub_f32_e32 v210, v210, v192
	v_pk_mul_f32 v[210:211], v[192:193], v[210:211] op_sel:[1,0]
	v_pk_mul_f32 v[208:209], v[192:193], v[208:209] op_sel:[1,0]
	v_pk_fma_f32 v[210:211], v[162:163], v[210:211], v[178:179]
	v_pk_fma_f32 v[208:209], v[160:161], v[208:209], v[176:177]
	v_pk_fma_f32 v[18:19], v[210:211], s[46:47], v[18:19] op_sel_hi:[1,0,1]
	v_pk_fma_f32 v[16:17], v[208:209], s[46:47], v[16:17] op_sel_hi:[1,0,1]
	global_store_dwordx4 v245, v[28:31], s[28:29] sc1
	global_store_dwordx4 v245, v[24:27], s[28:29] offset:64 sc1
	global_store_dwordx4 v245, v[20:23], s[28:29] offset:512 sc1
	global_store_dwordx4 v245, v[16:19], s[28:29] offset:576 sc1
	v_add_u32_e32 v245, 0x10000, v245
	s_waitcnt vmcnt(8)
; __device__ __forceinline__ int mk_tid(int wv) { return (wv << 6) | lane_now(); }
; #define PG8_BAR __builtin_amdgcn_s_barrier()
;     __device__ __forceinline__ void operator()(const f32x4 (&acc)[2][2][4][2], const Unit& u, int wr, int wc, int fr, int fq) const {
;     ...
;             for (int m = 0; m < 4; ++m) { const int row = row0 + ai * HALF + m * 16; const size_t ro = (size_t)row * 1024 + col0; const f32x2v st = *(const f32x2v*)(p.stats + 2 * row);
; #pragma unroll
;                 for (int bj = 0; bj < 2; ++bj)
; #pragma unroll
;                     for (int n = 0; n < 2; ++n) { const int c = col0 + bj * HALF + n * 16; const size_t off = ro + bj * HALF + n * 16;
;                         const f32x4 sv = *(const f32x4*)(p.src + off), gv = *(const f32x4*)(p.g + c), bv = *(const f32x4*)(p.b + c);
;                         const f32x4 hv = (sv - st.x) * st.y * gv + bv; *(f32x4*)(z + off) = hv * alpha + acc[ai][bj][m][n] * sc; }
;                 asm volatile("" ::: "memory"); }
; template <class Epi, class Sched, bool ALIGN_EPI = false, bool SP2 = false, bool F8 = false>
; __device__ __forceinline__ void gemm_phase(PG8_LAS unsigned char* lds, const Gemm g, const Sched& S, const Epi& E, const int wv) {
;     ...
;         if constexpr (ALIGN_EPI) { if (wr == 0) PG8_BAR; }
;         if constexpr (!Epi::AFTER_DRAIN) { const int t2_ = ::mk_tid(wv); const int l2_ = t2_ & 63;
;             E(acc, cur, wr, wc, l2_ & 15, l2_ >> 4); S.done(cur); }
;         if (!has_next) break;
; #pragma unroll
;         for (int a = 0; a < 2; ++a)
; #pragma unroll
;             for (int b = 0; b < 2; ++b)
; #pragma unroll
;                 for (int m = 0; m < 4; ++m)
; #pragma unroll
;                     for (int n = 0; n < 2; ++n) acc[a][b][m][n] = (f32x4){0.f, 0.f, 0.f, 0.f};
;         cur = nxt; cA = nA; cB = nB; ++ui;
;         if constexpr (ALIGN_EPI) { if (wr == 1) PG8_BAR; }
	v_sub_f32_e32 v213, v213, v194
	v_sub_f32_e32 v212, v212, v194
	v_sub_f32_e32 v215, v215, v194
	v_sub_f32_e32 v214, v214, v194
	v_pk_mul_f32 v[214:215], v[194:195], v[214:215] op_sel:[1,0]
	v_pk_mul_f32 v[212:213], v[194:195], v[212:213] op_sel:[1,0]
	v_pk_fma_f32 v[214:215], v[150:151], v[214:215], v[166:167]
	v_pk_fma_f32 v[212:213], v[148:149], v[212:213], v[164:165]
	v_pk_fma_f32 v[14:15], v[214:215], s[46:47], v[14:15] op_sel_hi:[1,0,1]
	v_pk_fma_f32 v[12:13], v[212:213], s[46:47], v[12:13] op_sel_hi:[1,0,1]
	v_sub_f32_e32 v217, v217, v194
	v_sub_f32_e32 v216, v216, v194
	v_sub_f32_e32 v219, v219, v194
	v_sub_f32_e32 v218, v218, v194
	v_pk_mul_f32 v[218:219], v[194:195], v[218:219] op_sel:[1,0]
	v_pk_mul_f32 v[216:217], v[194:195], v[216:217] op_sel:[1,0]
	v_pk_fma_f32 v[218:219], v[154:155], v[218:219], v[170:171]
	v_pk_fma_f32 v[216:217], v[152:153], v[216:217], v[168:169]
	v_pk_fma_f32 v[10:11], v[218:219], s[46:47], v[10:11] op_sel_hi:[1,0,1]
	v_pk_fma_f32 v[8:9], v[216:217], s[46:47], v[8:9] op_sel_hi:[1,0,1]
	v_sub_f32_e32 v221, v221, v194
	v_sub_f32_e32 v220, v220, v194
	v_sub_f32_e32 v223, v223, v194
	v_sub_f32_e32 v222, v222, v194
	v_pk_mul_f32 v[222:223], v[194:195], v[222:223] op_sel:[1,0]
	v_pk_mul_f32 v[220:221], v[194:195], v[220:221] op_sel:[1,0]
	v_pk_fma_f32 v[222:223], v[158:159], v[222:223], v[174:175]
	v_pk_fma_f32 v[220:221], v[156:157], v[220:221], v[172:173]
	v_pk_fma_f32 v[6:7], v[222:223], s[46:47], v[6:7] op_sel_hi:[1,0,1]
	v_pk_fma_f32 v[4:5], v[220:221], s[46:47], v[4:5] op_sel_hi:[1,0,1]
	v_sub_f32_e32 v225, v225, v194
	v_sub_f32_e32 v224, v224, v194
	v_sub_f32_e32 v227, v227, v194
	v_sub_f32_e32 v226, v226, v194
	v_pk_mul_f32 v[226:227], v[194:195], v[226:227] op_sel:[1,0]
	v_pk_mul_f32 v[224:225], v[194:195], v[224:225] op_sel:[1,0]
	v_pk_fma_f32 v[226:227], v[162:163], v[226:227], v[178:179]
	v_pk_fma_f32 v[224:225], v[160:161], v[224:225], v[176:177]
	v_pk_fma_f32 v[2:3], v[226:227], s[46:47], v[2:3] op_sel_hi:[1,0,1]
	v_pk_fma_f32 v[0:1], v[224:225], s[46:47], v[0:1] op_sel_hi:[1,0,1]
	global_store_dwordx4 v245, v[12:15], s[28:29] sc1
	global_store_dwordx4 v245, v[8:11], s[28:29] offset:64 sc1
	global_store_dwordx4 v245, v[4:7], s[28:29] offset:512 sc1
	global_store_dwordx4 v245, v[0:3], s[28:29] offset:576 sc1
	s_cbranch_vccnz .LBB0_770
	s_andn2_b64 vcc, exec, s[24:25]
	s_cbranch_vccnz .LBB0_769
	s_barrier
	s_branch .LBB0_769

;     __device__ __forceinline__ void operator()(const f32x4 (&acc)[2][2][4][2], const Unit& u, int wr, int wc, int fr, int fq) const {
;         int row0 = u.pm * BM + wr * 64 + fr, col0 = u.pn * BM + wc * 32 + 4 * fq; asm volatile("" : "+v"(row0), "+v"(col0));
;         typedef float f32x2v __attribute__((ext_vector_type(2)));
; #pragma unroll
;         for (int ai = 0; ai < 2; ++ai)
; #pragma unroll
;             for (int m = 0; m < 4; ++m) { const int row = row0 + ai * HALF + m * 16; const size_t ro = (size_t)row * 1024 + col0; const f32x2v st = *(const f32x2v*)(p.stats + 2 * row);
; #pragma unroll
;                 for (int bj = 0; bj < 2; ++bj)
; #pragma unroll
;                     for (int n = 0; n < 2; ++n) { const int c = col0 + bj * HALF + n * 16; const size_t off = ro + bj * HALF + n * 16;
;                         const f32x4 sv = *(const f32x4*)(p.src + off), gv = *(const f32x4*)(p.g + c), bv = *(const f32x4*)(p.b + c);
;                         const f32x4 hv = (sv - st.x) * st.y * gv + bv; *(f32x4*)(z + off) = hv * alpha + acc[ai][bj][m][n] * sc; }
;                 asm volatile("" ::: "memory"); }
.LBB0_983:
	s_lshl_b32 s18, s43, 8
	v_mbcnt_lo_u32_b32 v132, -1, 0
	v_mbcnt_hi_u32_b32 v132, -1, v132
	s_add_i32 s18, s18, s71
	v_and_or_b32 v138, v132, 15, s18
	s_lshl_b32 s18, s42, 8
	v_lshrrev_b32_e32 v132, 2, v132
	v_and_or_b32 v132, v132, 12, s18
	v_or_b32_e32 v136, s75, v132
	s_andn2_b64 vcc, exec, s[10:11]
	v_lshlrev_b32_e32 v244, 12, v138
	v_lshlrev_b32_e32 v246, 3, v138
	v_lshlrev_b32_e32 v247, 2, v136
	v_lshl_add_u32 v244, v136, 2, v244
	global_load_dwordx2 v[180:181], v246, s[28:29]
	global_load_dwordx2 v[182:183], v246, s[28:29] offset:128
	global_load_dwordx2 v[184:185], v246, s[28:29] offset:256
	global_load_dwordx2 v[186:187], v246, s[28:29] offset:384
	global_load_dwordx2 v[188:189], v246, s[28:29] offset:1024
	global_load_dwordx2 v[190:191], v246, s[28:29] offset:1152
	global_load_dwordx2 v[192:193], v246, s[28:29] offset:1280
	global_load_dwordx2 v[194:195], v246, s[28:29] offset:1408
	v_mov_b32_e32 v245, v244
	global_load_dwordx4 v[148:151], v247, s[20:21]
	global_load_dwordx4 v[152:155], v247, s[20:21] offset:64
	global_load_dwordx4 v[156:159], v247, s[20:21] offset:512
	global_load_dwordx4 v[160:163], v247, s[20:21] offset:576
	global_load_dwordx4 v[164:167], v247, s[22:23]
	global_load_dwordx4 v[168:171], v247, s[22:23] offset:64
	global_load_dwordx4 v[172:175], v247, s[22:23] offset:512
	global_load_dwordx4 v[176:179], v247, s[22:23] offset:576
	s_mov_b64 s[10:11], -1
	global_load_dwordx4 v[196:199], v244, s[26:27]
	global_load_dwordx4 v[200:203], v244, s[26:27] offset:64
	global_load_dwordx4 v[204:207], v244, s[26:27] offset:512
	global_load_dwordx4 v[208:211], v244, s[26:27] offset:576
	v_add_u32_e32 v244, 0x10000, v244
	global_load_dwordx4 v[212:215], v244, s[26:27]
	global_load_dwordx4 v[216:219], v244, s[26:27] offset:64
	global_load_dwordx4 v[220:223], v244, s[26:27] offset:512
	global_load_dwordx4 v[224:227], v244, s[26:27] offset:576
	v_add_u32_e32 v244, 0x10000, v244
	global_load_dwordx4 v[228:231], v244, s[26:27]
	global_load_dwordx4 v[232:235], v244, s[26:27] offset:64
	global_load_dwordx4 v[236:239], v244, s[26:27] offset:512
	global_load_dwordx4 v[240:243], v244, s[26:27] offset:576
	v_add_u32_e32 v244, 0x10000, v244
	s_waitcnt vmcnt(8)
	v_sub_f32_e32 v197, v197, v180
	v_sub_f32_e32 v196, v196, v180
	v_sub_f32_e32 v199, v199, v180
	v_sub_f32_e32 v198, v198, v180
	v_pk_mul_f32 v[198:199], v[180:181], v[198:199] op_sel:[1,0]
	v_pk_mul_f32 v[196:197], v[180:181], v[196:197] op_sel:[1,0]
	v_pk_fma_f32 v[198:199], v[150:151], v[198:199], v[166:167]
	v_pk_fma_f32 v[196:197], v[148:149], v[196:197], v[164:165]
	v_pk_mul_f32 v[196:197], v[196:197], s[48:49] op_sel_hi:[1,0]
	v_pk_mul_f32 v[198:199], v[198:199], s[48:49] op_sel_hi:[1,0]
	v_pk_fma_f32 v[124:125], v[124:125], s[50:51], v[196:197] op_sel_hi:[1,0,1]
	v_pk_fma_f32 v[126:127], v[126:127], s[50:51], v[198:199] op_sel_hi:[1,0,1]
	v_sub_f32_e32 v201, v201, v180
	v_sub_f32_e32 v200, v200, v180
	v_sub_f32_e32 v203, v203, v180
	v_sub_f32_e32 v202, v202, v180
	v_pk_mul_f32 v[202:203], v[180:181], v[202:203] op_sel:[1,0]
	v_pk_mul_f32 v[200:201], v[180:181], v[200:201] op_sel:[1,0]
	v_pk_fma_f32 v[202:203], v[154:155], v[202:203], v[170:171]
	v_pk_fma_f32 v[200:201], v[152:153], v[200:201], v[168:169]
	v_pk_mul_f32 v[200:201], v[200:201], s[48:49] op_sel_hi:[1,0]
	v_pk_mul_f32 v[202:203], v[202:203], s[48:49] op_sel_hi:[1,0]
	v_pk_fma_f32 v[120:121], v[120:121], s[50:51], v[200:201] op_sel_hi:[1,0,1]
	v_pk_fma_f32 v[122:123], v[122:123], s[50:51], v[202:203] op_sel_hi:[1,0,1]
	v_sub_f32_e32 v205, v205, v180
	v_sub_f32_e32 v204, v204, v180
	v_sub_f32_e32 v207, v207, v180
	v_sub_f32_e32 v206, v206, v180
	v_pk_mul_f32 v[206:207], v[180:181], v[206:207] op_sel:[1,0]
	v_pk_mul_f32 v[204:205], v[180:181], v[204:205] op_sel:[1,0]
	v_pk_fma_f32 v[206:207], v[158:159], v[206:207], v[174:175]
	v_pk_fma_f32 v[204:205], v[156:157], v[204:205], v[172:173]
	v_pk_mul_f32 v[204:205], v[204:205], s[48:49] op_sel_hi:[1,0]
	v_pk_mul_f32 v[206:207], v[206:207], s[48:49] op_sel_hi:[1,0]
	v_pk_fma_f32 v[116:117], v[116:117], s[50:51], v[204:205] op_sel_hi:[1,0,1]
	v_pk_fma_f32 v[118:119], v[118:119], s[50:51], v[206:207] op_sel_hi:[1,0,1]
	v_sub_f32_e32 v209, v209, v180
	v_sub_f32_e32 v208, v208, v180
	v_sub_f32_e32 v211, v211, v180
	v_sub_f32_e32 v210, v210, v180
	v_pk_mul_f32 v[210:211], v[180:181], v[210:211] op_sel:[1,0]
	v_pk_mul_f32 v[208:209], v[180:181], v[208:209] op_sel:[1,0]
	v_pk_fma_f32 v[210:211], v[162:163], v[210:211], v[178:179]
	v_pk_fma_f32 v[208:209], v[160:161], v[208:209], v[176:177]
	v_pk_mul_f32 v[208:209], v[208:209], s[48:49] op_sel_hi:[1,0]
	v_pk_mul_f32 v[210:211], v[210:211], s[48:49] op_sel_hi:[1,0]
	v_pk_fma_f32 v[112:113], v[112:113], s[50:51], v[208:209] op_sel_hi:[1,0,1]
	v_pk_fma_f32 v[114:115], v[114:115], s[50:51], v[210:211] op_sel_hi:[1,0,1]
	global_store_dwordx4 v245, v[124:127], s[44:45] sc1
	global_store_dwordx4 v245, v[120:123], s[44:45] offset:64 sc1
	global_store_dwordx4 v245, v[116:119], s[44:45] offset:512 sc1
	global_store_dwordx4 v245, v[112:115], s[44:45] offset:576 sc1
	v_add_u32_e32 v245, 0x10000, v245
	global_load_dwordx4 v[196:199], v244, s[26:27]
	global_load_dwordx4 v[200:203], v244, s[26:27] offset:64
	global_load_dwordx4 v[204:207], v244, s[26:27] offset:512
	global_load_dwordx4 v[208:211], v244, s[26:27] offset:576
	v_add_u32_e32 v244, 0x50000, v244
	s_waitcnt vmcnt(12)
;     __device__ __forceinline__ void operator()(const f32x4 (&acc)[2][2][4][2], const Unit& u, int wr, int wc, int fr, int fq) const {
;     ...
;             for (int m = 0; m < 4; ++m) { const int row = row0 + ai * HALF + m * 16; const size_t ro = (size_t)row * 1024 + col0; const f32x2v st = *(const f32x2v*)(p.stats + 2 * row);
; #pragma unroll
;                 for (int bj = 0; bj < 2; ++bj)
; #pragma unroll
;                     for (int n = 0; n < 2; ++n) { const int c = col0 + bj * HALF + n * 16; const size_t off = ro + bj * HALF + n * 16;
;                         const f32x4 sv = *(const f32x4*)(p.src + off), gv = *(const f32x4*)(p.g + c), bv = *(const f32x4*)(p.b + c);
;                         const f32x4 hv = (sv - st.x) * st.y * gv + bv; *(f32x4*)(z + off) = hv * alpha + acc[ai][bj][m][n] * sc; }
;                 asm volatile("" ::: "memory"); }
	v_sub_f32_e32 v213, v213, v182
	v_sub_f32_e32 v212, v212, v182
	v_sub_f32_e32 v215, v215, v182
	v_sub_f32_e32 v214, v214, v182
	v_pk_mul_f32 v[214:215], v[182:183], v[214:215] op_sel:[1,0]
	v_pk_mul_f32 v[212:213], v[182:183], v[212:213] op_sel:[1,0]
	v_pk_fma_f32 v[214:215], v[150:151], v[214:215], v[166:167]
	v_pk_fma_f32 v[212:213], v[148:149], v[212:213], v[164:165]
	v_pk_mul_f32 v[212:213], v[212:213], s[48:49] op_sel_hi:[1,0]
	v_pk_mul_f32 v[214:215], v[214:215], s[48:49] op_sel_hi:[1,0]
	v_pk_fma_f32 v[108:109], v[108:109], s[50:51], v[212:213] op_sel_hi:[1,0,1]
	v_pk_fma_f32 v[110:111], v[110:111], s[50:51], v[214:215] op_sel_hi:[1,0,1]
	v_sub_f32_e32 v217, v217, v182
	v_sub_f32_e32 v216, v216, v182
	v_sub_f32_e32 v219, v219, v182
	v_sub_f32_e32 v218, v218, v182
	v_pk_mul_f32 v[218:219], v[182:183], v[218:219] op_sel:[1,0]
	v_pk_mul_f32 v[216:217], v[182:183], v[216:217] op_sel:[1,0]
	v_pk_fma_f32 v[218:219], v[154:155], v[218:219], v[170:171]
	v_pk_fma_f32 v[216:217], v[152:153], v[216:217], v[168:169]
	v_pk_mul_f32 v[216:217], v[216:217], s[48:49] op_sel_hi:[1,0]
	v_pk_mul_f32 v[218:219], v[218:219], s[48:49] op_sel_hi:[1,0]
	v_pk_fma_f32 v[104:105], v[104:105], s[50:51], v[216:217] op_sel_hi:[1,0,1]
	v_pk_fma_f32 v[106:107], v[106:107], s[50:51], v[218:219] op_sel_hi:[1,0,1]
	v_sub_f32_e32 v221, v221, v182
	v_sub_f32_e32 v220, v220, v182
	v_sub_f32_e32 v223, v223, v182
	v_sub_f32_e32 v222, v222, v182
	v_pk_mul_f32 v[222:223], v[182:183], v[222:223] op_sel:[1,0]
	v_pk_mul_f32 v[220:221], v[182:183], v[220:221] op_sel:[1,0]
	v_pk_fma_f32 v[222:223], v[158:159], v[222:223], v[174:175]
	v_pk_fma_f32 v[220:221], v[156:157], v[220:221], v[172:173]
	v_pk_mul_f32 v[220:221], v[220:221], s[48:49] op_sel_hi:[1,0]
	v_pk_mul_f32 v[222:223], v[222:223], s[48:49] op_sel_hi:[1,0]
	v_pk_fma_f32 v[100:101], v[100:101], s[50:51], v[220:221] op_sel_hi:[1,0,1]
	v_pk_fma_f32 v[102:103], v[102:103], s[50:51], v[222:223] op_sel_hi:[1,0,1]
	v_sub_f32_e32 v225, v225, v182
	v_sub_f32_e32 v224, v224, v182
	v_sub_f32_e32 v227, v227, v182
	v_sub_f32_e32 v226, v226, v182
	v_pk_mul_f32 v[226:227], v[182:183], v[226:227] op_sel:[1,0]
	v_pk_mul_f32 v[224:225], v[182:183], v[224:225] op_sel:[1,0]
	v_pk_fma_f32 v[226:227], v[162:163], v[226:227], v[178:179]
	v_pk_fma_f32 v[224:225], v[160:161], v[224:225], v[176:177]
	v_pk_mul_f32 v[224:225], v[224:225], s[48:49] op_sel_hi:[1,0]
	v_pk_mul_f32 v[226:227], v[226:227], s[48:49] op_sel_hi:[1,0]
	v_pk_fma_f32 v[96:97], v[96:97], s[50:51], v[224:225] op_sel_hi:[1,0,1]
	v_pk_fma_f32 v[98:99], v[98:99], s[50:51], v[226:227] op_sel_hi:[1,0,1]
	global_store_dwordx4 v245, v[108:111], s[44:45] sc1
	global_store_dwordx4 v245, v[104:107], s[44:45] offset:64 sc1
	global_store_dwordx4 v245, v[100:103], s[44:45] offset:512 sc1
	global_store_dwordx4 v245, v[96:99], s[44:45] offset:576 sc1
	v_add_u32_e32 v245, 0x10000, v245
	global_load_dwordx4 v[212:215], v244, s[26:27]
	global_load_dwordx4 v[216:219], v244, s[26:27] offset:64
	global_load_dwordx4 v[220:223], v244, s[26:27] offset:512
	global_load_dwordx4 v[224:227], v244, s[26:27] offset:576
	v_add_u32_e32 v244, 0x10000, v244
	s_waitcnt vmcnt(16)
	v_sub_f32_e32 v229, v229, v184
	v_sub_f32_e32 v228, v228, v184
	v_sub_f32_e32 v231, v231, v184
	v_sub_f32_e32 v230, v230, v184
	v_pk_mul_f32 v[230:231], v[184:185], v[230:231] op_sel:[1,0]
	v_pk_mul_f32 v[228:229], v[184:185], v[228:229] op_sel:[1,0]
	v_pk_fma_f32 v[230:231], v[150:151], v[230:231], v[166:167]
	v_pk_fma_f32 v[228:229], v[148:149], v[228:229], v[164:165]
	v_pk_mul_f32 v[228:229], v[228:229], s[48:49] op_sel_hi:[1,0]
	v_pk_mul_f32 v[230:231], v[230:231], s[48:49] op_sel_hi:[1,0]
	v_pk_fma_f32 v[92:93], v[92:93], s[50:51], v[228:229] op_sel_hi:[1,0,1]
	v_pk_fma_f32 v[94:95], v[94:95], s[50:51], v[230:231] op_sel_hi:[1,0,1]
	v_sub_f32_e32 v233, v233, v184
	v_sub_f32_e32 v232, v232, v184
	v_sub_f32_e32 v235, v235, v184
	v_sub_f32_e32 v234, v234, v184
	v_pk_mul_f32 v[234:235], v[184:185], v[234:235] op_sel:[1,0]
	v_pk_mul_f32 v[232:233], v[184:185], v[232:233] op_sel:[1,0]
	v_pk_fma_f32 v[234:235], v[154:155], v[234:235], v[170:171]
	v_pk_fma_f32 v[232:233], v[152:153], v[232:233], v[168:169]
	v_pk_mul_f32 v[232:233], v[232:233], s[48:49] op_sel_hi:[1,0]
	v_pk_mul_f32 v[234:235], v[234:235], s[48:49] op_sel_hi:[1,0]
	v_pk_fma_f32 v[88:89], v[88:89], s[50:51], v[232:233] op_sel_hi:[1,0,1]
	v_pk_fma_f32 v[90:91], v[90:91], s[50:51], v[234:235] op_sel_hi:[1,0,1]
	v_sub_f32_e32 v237, v237, v184
	v_sub_f32_e32 v236, v236, v184
	v_sub_f32_e32 v239, v239, v184
	v_sub_f32_e32 v238, v238, v184
	v_pk_mul_f32 v[238:239], v[184:185], v[238:239] op_sel:[1,0]
	v_pk_mul_f32 v[236:237], v[184:185], v[236:237] op_sel:[1,0]
	v_pk_fma_f32 v[238:239], v[158:159], v[238:239], v[174:175]
	v_pk_fma_f32 v[236:237], v[156:157], v[236:237], v[172:173]
	v_pk_mul_f32 v[236:237], v[236:237], s[48:49] op_sel_hi:[1,0]
	v_pk_mul_f32 v[238:239], v[238:239], s[48:49] op_sel_hi:[1,0]
	v_pk_fma_f32 v[84:85], v[84:85], s[50:51], v[236:237] op_sel_hi:[1,0,1]
	v_pk_fma_f32 v[86:87], v[86:87], s[50:51], v[238:239] op_sel_hi:[1,0,1]
	v_sub_f32_e32 v241, v241, v184
	v_sub_f32_e32 v240, v240, v184
	v_sub_f32_e32 v243, v243, v184
	v_sub_f32_e32 v242, v242, v184
	v_pk_mul_f32 v[242:243], v[184:185], v[242:243] op_sel:[1,0]
	v_pk_mul_f32 v[240:241], v[184:185], v[240:241] op_sel:[1,0]
	v_pk_fma_f32 v[242:243], v[162:163], v[242:243], v[178:179]
	v_pk_fma_f32 v[240:241], v[160:161], v[240:241], v[176:177]
	v_pk_mul_f32 v[240:241], v[240:241], s[48:49] op_sel_hi:[1,0]
	v_pk_mul_f32 v[242:243], v[242:243], s[48:49] op_sel_hi:[1,0]
	v_pk_fma_f32 v[80:81], v[80:81], s[50:51], v[240:241] op_sel_hi:[1,0,1]
	v_pk_fma_f32 v[82:83], v[82:83], s[50:51], v[242:243] op_sel_hi:[1,0,1]
	global_store_dwordx4 v245, v[92:95], s[44:45] sc1
	global_store_dwordx4 v245, v[88:91], s[44:45] offset:64 sc1
	global_store_dwordx4 v245, v[84:87], s[44:45] offset:512 sc1
	global_store_dwordx4 v245, v[80:83], s[44:45] offset:576 sc1
	v_add_u32_e32 v245, 0x10000, v245
	global_load_dwordx4 v[228:231], v244, s[26:27]
	global_load_dwordx4 v[232:235], v244, s[26:27] offset:64
	global_load_dwordx4 v[236:239], v244, s[26:27] offset:512
	global_load_dwordx4 v[240:243], v244, s[26:27] offset:576
	v_add_u32_e32 v244, 0x10000, v244
	s_waitcnt vmcnt(16)
;     __device__ __forceinline__ void operator()(const f32x4 (&acc)[2][2][4][2], const Unit& u, int wr, int wc, int fr, int fq) const {
;     ...
;             for (int m = 0; m < 4; ++m) { const int row = row0 + ai * HALF + m * 16; const size_t ro = (size_t)row * 1024 + col0; const f32x2v st = *(const f32x2v*)(p.stats + 2 * row);
; #pragma unroll
;                 for (int bj = 0; bj < 2; ++bj)
; #pragma unroll
;                     for (int n = 0; n < 2; ++n) { const int c = col0 + bj * HALF + n * 16; const size_t off = ro + bj * HALF + n * 16;
;                         const f32x4 sv = *(const f32x4*)(p.src + off), gv = *(const f32x4*)(p.g + c), bv = *(const f32x4*)(p.b + c);
;                         const f32x4 hv = (sv - st.x) * st.y * gv + bv; *(f32x4*)(z + off) = hv * alpha + acc[ai][bj][m][n] * sc; }
;                 asm volatile("" ::: "memory"); }
	v_sub_f32_e32 v197, v197, v186
	v_sub_f32_e32 v196, v196, v186
	v_sub_f32_e32 v199, v199, v186
	v_sub_f32_e32 v198, v198, v186
	v_pk_mul_f32 v[198:199], v[186:187], v[198:199] op_sel:[1,0]
	v_pk_mul_f32 v[196:197], v[186:187], v[196:197] op_sel:[1,0]
	v_pk_fma_f32 v[198:199], v[150:151], v[198:199], v[166:167]
	v_pk_fma_f32 v[196:197], v[148:149], v[196:197], v[164:165]
	v_pk_mul_f32 v[196:197], v[196:197], s[48:49] op_sel_hi:[1,0]
	v_pk_mul_f32 v[198:199], v[198:199], s[48:49] op_sel_hi:[1,0]
	v_pk_fma_f32 v[76:77], v[76:77], s[50:51], v[196:197] op_sel_hi:[1,0,1]
	v_pk_fma_f32 v[78:79], v[78:79], s[50:51], v[198:199] op_sel_hi:[1,0,1]
	v_sub_f32_e32 v201, v201, v186
	v_sub_f32_e32 v200, v200, v186
	v_sub_f32_e32 v203, v203, v186
	v_sub_f32_e32 v202, v202, v186
	v_pk_mul_f32 v[202:203], v[186:187], v[202:203] op_sel:[1,0]
	v_pk_mul_f32 v[200:201], v[186:187], v[200:201] op_sel:[1,0]
	v_pk_fma_f32 v[202:203], v[154:155], v[202:203], v[170:171]
	v_pk_fma_f32 v[200:201], v[152:153], v[200:201], v[168:169]
	v_pk_mul_f32 v[200:201], v[200:201], s[48:49] op_sel_hi:[1,0]
	v_pk_mul_f32 v[202:203], v[202:203], s[48:49] op_sel_hi:[1,0]
	v_pk_fma_f32 v[72:73], v[72:73], s[50:51], v[200:201] op_sel_hi:[1,0,1]
	v_pk_fma_f32 v[74:75], v[74:75], s[50:51], v[202:203] op_sel_hi:[1,0,1]
	v_sub_f32_e32 v205, v205, v186
	v_sub_f32_e32 v204, v204, v186
	v_sub_f32_e32 v207, v207, v186
	v_sub_f32_e32 v206, v206, v186
	v_pk_mul_f32 v[206:207], v[186:187], v[206:207] op_sel:[1,0]
	v_pk_mul_f32 v[204:205], v[186:187], v[204:205] op_sel:[1,0]
	v_pk_fma_f32 v[206:207], v[158:159], v[206:207], v[174:175]
	v_pk_fma_f32 v[204:205], v[156:157], v[204:205], v[172:173]
	v_pk_mul_f32 v[204:205], v[204:205], s[48:49] op_sel_hi:[1,0]
	v_pk_mul_f32 v[206:207], v[206:207], s[48:49] op_sel_hi:[1,0]
	v_pk_fma_f32 v[68:69], v[68:69], s[50:51], v[204:205] op_sel_hi:[1,0,1]
	v_pk_fma_f32 v[70:71], v[70:71], s[50:51], v[206:207] op_sel_hi:[1,0,1]
	v_sub_f32_e32 v209, v209, v186
	v_sub_f32_e32 v208, v208, v186
	v_sub_f32_e32 v211, v211, v186
	v_sub_f32_e32 v210, v210, v186
	v_pk_mul_f32 v[210:211], v[186:187], v[210:211] op_sel:[1,0]
	v_pk_mul_f32 v[208:209], v[186:187], v[208:209] op_sel:[1,0]
	v_pk_fma_f32 v[210:211], v[162:163], v[210:211], v[178:179]
	v_pk_fma_f32 v[208:209], v[160:161], v[208:209], v[176:177]
	v_pk_mul_f32 v[208:209], v[208:209], s[48:49] op_sel_hi:[1,0]
	v_pk_mul_f32 v[210:211], v[210:211], s[48:49] op_sel_hi:[1,0]
	v_pk_fma_f32 v[64:65], v[64:65], s[50:51], v[208:209] op_sel_hi:[1,0,1]
	v_pk_fma_f32 v[66:67], v[66:67], s[50:51], v[210:211] op_sel_hi:[1,0,1]
	global_store_dwordx4 v245, v[76:79], s[44:45] sc1
	global_store_dwordx4 v245, v[72:75], s[44:45] offset:64 sc1
	global_store_dwordx4 v245, v[68:71], s[44:45] offset:512 sc1
	global_store_dwordx4 v245, v[64:67], s[44:45] offset:576 sc1
	v_add_u32_e32 v245, 0x50000, v245
	global_load_dwordx4 v[196:199], v244, s[26:27]
	global_load_dwordx4 v[200:203], v244, s[26:27] offset:64
	global_load_dwordx4 v[204:207], v244, s[26:27] offset:512
	global_load_dwordx4 v[208:211], v244, s[26:27] offset:576
	v_add_u32_e32 v244, 0x10000, v244
	s_waitcnt vmcnt(16)
	v_sub_f32_e32 v213, v213, v188
	v_sub_f32_e32 v212, v212, v188
	v_sub_f32_e32 v215, v215, v188
	v_sub_f32_e32 v214, v214, v188
	v_pk_mul_f32 v[214:215], v[188:189], v[214:215] op_sel:[1,0]
	v_pk_mul_f32 v[212:213], v[188:189], v[212:213] op_sel:[1,0]
	v_pk_fma_f32 v[214:215], v[150:151], v[214:215], v[166:167]
	v_pk_fma_f32 v[212:213], v[148:149], v[212:213], v[164:165]
	v_pk_mul_f32 v[212:213], v[212:213], s[48:49] op_sel_hi:[1,0]
	v_pk_mul_f32 v[214:215], v[214:215], s[48:49] op_sel_hi:[1,0]
	v_pk_fma_f32 v[60:61], v[60:61], s[50:51], v[212:213] op_sel_hi:[1,0,1]
	v_pk_fma_f32 v[62:63], v[62:63], s[50:51], v[214:215] op_sel_hi:[1,0,1]
	v_sub_f32_e32 v217, v217, v188
	v_sub_f32_e32 v216, v216, v188
	v_sub_f32_e32 v219, v219, v188
	v_sub_f32_e32 v218, v218, v188
	v_pk_mul_f32 v[218:219], v[188:189], v[218:219] op_sel:[1,0]
	v_pk_mul_f32 v[216:217], v[188:189], v[216:217] op_sel:[1,0]
	v_pk_fma_f32 v[218:219], v[154:155], v[218:219], v[170:171]
	v_pk_fma_f32 v[216:217], v[152:153], v[216:217], v[168:169]
	v_pk_mul_f32 v[216:217], v[216:217], s[48:49] op_sel_hi:[1,0]
	v_pk_mul_f32 v[218:219], v[218:219], s[48:49] op_sel_hi:[1,0]
	v_pk_fma_f32 v[56:57], v[56:57], s[50:51], v[216:217] op_sel_hi:[1,0,1]
	v_pk_fma_f32 v[58:59], v[58:59], s[50:51], v[218:219] op_sel_hi:[1,0,1]
	v_sub_f32_e32 v221, v221, v188
	v_sub_f32_e32 v220, v220, v188
	v_sub_f32_e32 v223, v223, v188
	v_sub_f32_e32 v222, v222, v188
	v_pk_mul_f32 v[222:223], v[188:189], v[222:223] op_sel:[1,0]
	v_pk_mul_f32 v[220:221], v[188:189], v[220:221] op_sel:[1,0]
	v_pk_fma_f32 v[222:223], v[158:159], v[222:223], v[174:175]
	v_pk_fma_f32 v[220:221], v[156:157], v[220:221], v[172:173]
	v_pk_mul_f32 v[220:221], v[220:221], s[48:49] op_sel_hi:[1,0]
	v_pk_mul_f32 v[222:223], v[222:223], s[48:49] op_sel_hi:[1,0]
	v_pk_fma_f32 v[52:53], v[52:53], s[50:51], v[220:221] op_sel_hi:[1,0,1]
	v_pk_fma_f32 v[54:55], v[54:55], s[50:51], v[222:223] op_sel_hi:[1,0,1]
	v_sub_f32_e32 v225, v225, v188
	v_sub_f32_e32 v224, v224, v188
	v_sub_f32_e32 v227, v227, v188
	v_sub_f32_e32 v226, v226, v188
	v_pk_mul_f32 v[226:227], v[188:189], v[226:227] op_sel:[1,0]
	v_pk_mul_f32 v[224:225], v[188:189], v[224:225] op_sel:[1,0]
	v_pk_fma_f32 v[226:227], v[162:163], v[226:227], v[178:179]
	v_pk_fma_f32 v[224:225], v[160:161], v[224:225], v[176:177]
	v_pk_mul_f32 v[224:225], v[224:225], s[48:49] op_sel_hi:[1,0]
	v_pk_mul_f32 v[226:227], v[226:227], s[48:49] op_sel_hi:[1,0]
	v_pk_fma_f32 v[48:49], v[48:49], s[50:51], v[224:225] op_sel_hi:[1,0,1]
	v_pk_fma_f32 v[50:51], v[50:51], s[50:51], v[226:227] op_sel_hi:[1,0,1]
	global_store_dwordx4 v245, v[60:63], s[44:45] sc1
	global_store_dwordx4 v245, v[56:59], s[44:45] offset:64 sc1
	global_store_dwordx4 v245, v[52:55], s[44:45] offset:512 sc1
	global_store_dwordx4 v245, v[48:51], s[44:45] offset:576 sc1
	v_add_u32_e32 v245, 0x10000, v245
	global_load_dwordx4 v[212:215], v244, s[26:27]
	global_load_dwordx4 v[216:219], v244, s[26:27] offset:64
	global_load_dwordx4 v[220:223], v244, s[26:27] offset:512
	global_load_dwordx4 v[224:227], v244, s[26:27] offset:576
	s_waitcnt vmcnt(16)
;     __device__ __forceinline__ void operator()(const f32x4 (&acc)[2][2][4][2], const Unit& u, int wr, int wc, int fr, int fq) const {
;     ...
;             for (int m = 0; m < 4; ++m) { const int row = row0 + ai * HALF + m * 16; const size_t ro = (size_t)row * 1024 + col0; const f32x2v st = *(const f32x2v*)(p.stats + 2 * row);
; #pragma unroll
;                 for (int bj = 0; bj < 2; ++bj)
; #pragma unroll
;                     for (int n = 0; n < 2; ++n) { const int c = col0 + bj * HALF + n * 16; const size_t off = ro + bj * HALF + n * 16;
;                         const f32x4 sv = *(const f32x4*)(p.src + off), gv = *(const f32x4*)(p.g + c), bv = *(const f32x4*)(p.b + c);
;                         const f32x4 hv = (sv - st.x) * st.y * gv + bv; *(f32x4*)(z + off) = hv * alpha + acc[ai][bj][m][n] * sc; }
;                 asm volatile("" ::: "memory"); }
	v_sub_f32_e32 v229, v229, v190
	v_sub_f32_e32 v228, v228, v190
	v_sub_f32_e32 v231, v231, v190
	v_sub_f32_e32 v230, v230, v190
	v_pk_mul_f32 v[230:231], v[190:191], v[230:231] op_sel:[1,0]
	v_pk_mul_f32 v[228:229], v[190:191], v[228:229] op_sel:[1,0]
	v_pk_fma_f32 v[230:231], v[150:151], v[230:231], v[166:167]
	v_pk_fma_f32 v[228:229], v[148:149], v[228:229], v[164:165]
	v_pk_mul_f32 v[228:229], v[228:229], s[48:49] op_sel_hi:[1,0]
	v_pk_mul_f32 v[230:231], v[230:231], s[48:49] op_sel_hi:[1,0]
	v_pk_fma_f32 v[44:45], v[44:45], s[50:51], v[228:229] op_sel_hi:[1,0,1]
	v_pk_fma_f32 v[46:47], v[46:47], s[50:51], v[230:231] op_sel_hi:[1,0,1]
	v_sub_f32_e32 v233, v233, v190
	v_sub_f32_e32 v232, v232, v190
	v_sub_f32_e32 v235, v235, v190
	v_sub_f32_e32 v234, v234, v190
	v_pk_mul_f32 v[234:235], v[190:191], v[234:235] op_sel:[1,0]
	v_pk_mul_f32 v[232:233], v[190:191], v[232:233] op_sel:[1,0]
	v_pk_fma_f32 v[234:235], v[154:155], v[234:235], v[170:171]
	v_pk_fma_f32 v[232:233], v[152:153], v[232:233], v[168:169]
	v_pk_mul_f32 v[232:233], v[232:233], s[48:49] op_sel_hi:[1,0]
	v_pk_mul_f32 v[234:235], v[234:235], s[48:49] op_sel_hi:[1,0]
	v_pk_fma_f32 v[40:41], v[40:41], s[50:51], v[232:233] op_sel_hi:[1,0,1]
	v_pk_fma_f32 v[42:43], v[42:43], s[50:51], v[234:235] op_sel_hi:[1,0,1]
	v_sub_f32_e32 v237, v237, v190
	v_sub_f32_e32 v236, v236, v190
	v_sub_f32_e32 v239, v239, v190
	v_sub_f32_e32 v238, v238, v190
	v_pk_mul_f32 v[238:239], v[190:191], v[238:239] op_sel:[1,0]
	v_pk_mul_f32 v[236:237], v[190:191], v[236:237] op_sel:[1,0]
	v_pk_fma_f32 v[238:239], v[158:159], v[238:239], v[174:175]
	v_pk_fma_f32 v[236:237], v[156:157], v[236:237], v[172:173]
	v_pk_mul_f32 v[236:237], v[236:237], s[48:49] op_sel_hi:[1,0]
	v_pk_mul_f32 v[238:239], v[238:239], s[48:49] op_sel_hi:[1,0]
	v_pk_fma_f32 v[36:37], v[36:37], s[50:51], v[236:237] op_sel_hi:[1,0,1]
	v_pk_fma_f32 v[38:39], v[38:39], s[50:51], v[238:239] op_sel_hi:[1,0,1]
	v_sub_f32_e32 v241, v241, v190
	v_sub_f32_e32 v240, v240, v190
	v_sub_f32_e32 v243, v243, v190
	v_sub_f32_e32 v242, v242, v190
	v_pk_mul_f32 v[242:243], v[190:191], v[242:243] op_sel:[1,0]
	v_pk_mul_f32 v[240:241], v[190:191], v[240:241] op_sel:[1,0]
	v_pk_fma_f32 v[242:243], v[162:163], v[242:243], v[178:179]
	v_pk_fma_f32 v[240:241], v[160:161], v[240:241], v[176:177]
	v_pk_mul_f32 v[240:241], v[240:241], s[48:49] op_sel_hi:[1,0]
	v_pk_mul_f32 v[242:243], v[242:243], s[48:49] op_sel_hi:[1,0]
	v_pk_fma_f32 v[32:33], v[32:33], s[50:51], v[240:241] op_sel_hi:[1,0,1]
	v_pk_fma_f32 v[34:35], v[34:35], s[50:51], v[242:243] op_sel_hi:[1,0,1]
	global_store_dwordx4 v245, v[44:47], s[44:45] sc1
	global_store_dwordx4 v245, v[40:43], s[44:45] offset:64 sc1
	global_store_dwordx4 v245, v[36:39], s[44:45] offset:512 sc1
	global_store_dwordx4 v245, v[32:35], s[44:45] offset:576 sc1
	v_add_u32_e32 v245, 0x10000, v245
	s_waitcnt vmcnt(12)
	v_sub_f32_e32 v197, v197, v192
	v_sub_f32_e32 v196, v196, v192
	v_sub_f32_e32 v199, v199, v192
	v_sub_f32_e32 v198, v198, v192
	v_pk_mul_f32 v[198:199], v[192:193], v[198:199] op_sel:[1,0]
	v_pk_mul_f32 v[196:197], v[192:193], v[196:197] op_sel:[1,0]
	v_pk_fma_f32 v[198:199], v[150:151], v[198:199], v[166:167]
	v_pk_fma_f32 v[196:197], v[148:149], v[196:197], v[164:165]
	v_pk_mul_f32 v[196:197], v[196:197], s[48:49] op_sel_hi:[1,0]
	v_pk_mul_f32 v[198:199], v[198:199], s[48:49] op_sel_hi:[1,0]
	v_pk_fma_f32 v[28:29], v[28:29], s[50:51], v[196:197] op_sel_hi:[1,0,1]
	v_pk_fma_f32 v[30:31], v[30:31], s[50:51], v[198:199] op_sel_hi:[1,0,1]
	v_sub_f32_e32 v201, v201, v192
	v_sub_f32_e32 v200, v200, v192
	v_sub_f32_e32 v203, v203, v192
	v_sub_f32_e32 v202, v202, v192
	v_pk_mul_f32 v[202:203], v[192:193], v[202:203] op_sel:[1,0]
	v_pk_mul_f32 v[200:201], v[192:193], v[200:201] op_sel:[1,0]
	v_pk_fma_f32 v[202:203], v[154:155], v[202:203], v[170:171]
	v_pk_fma_f32 v[200:201], v[152:153], v[200:201], v[168:169]
	v_pk_mul_f32 v[200:201], v[200:201], s[48:49] op_sel_hi:[1,0]
	v_pk_mul_f32 v[202:203], v[202:203], s[48:49] op_sel_hi:[1,0]
	v_pk_fma_f32 v[24:25], v[24:25], s[50:51], v[200:201] op_sel_hi:[1,0,1]
	v_pk_fma_f32 v[26:27], v[26:27], s[50:51], v[202:203] op_sel_hi:[1,0,1]
	v_sub_f32_e32 v205, v205, v192
	v_sub_f32_e32 v204, v204, v192
	v_sub_f32_e32 v207, v207, v192
	v_sub_f32_e32 v206, v206, v192
	v_pk_mul_f32 v[206:207], v[192:193], v[206:207] op_sel:[1,0]
	v_pk_mul_f32 v[204:205], v[192:193], v[204:205] op_sel:[1,0]
	v_pk_fma_f32 v[206:207], v[158:159], v[206:207], v[174:175]
	v_pk_fma_f32 v[204:205], v[156:157], v[204:205], v[172:173]
	v_pk_mul_f32 v[204:205], v[204:205], s[48:49] op_sel_hi:[1,0]
	v_pk_mul_f32 v[206:207], v[206:207], s[48:49] op_sel_hi:[1,0]
	v_pk_fma_f32 v[20:21], v[20:21], s[50:51], v[204:205] op_sel_hi:[1,0,1]
	v_pk_fma_f32 v[22:23], v[22:23], s[50:51], v[206:207] op_sel_hi:[1,0,1]
	v_sub_f32_e32 v209, v209, v192
	v_sub_f32_e32 v208, v208, v192
	v_sub_f32_e32 v211, v211, v192
	v_sub_f32_e32 v210, v210, v192
	v_pk_mul_f32 v[210:211], v[192:193], v[210:211] op_sel:[1,0]
	v_pk_mul_f32 v[208:209], v[192:193], v[208:209] op_sel:[1,0]
	v_pk_fma_f32 v[210:211], v[162:163], v[210:211], v[178:179]
	v_pk_fma_f32 v[208:209], v[160:161], v[208:209], v[176:177]
	v_pk_mul_f32 v[208:209], v[208:209], s[48:49] op_sel_hi:[1,0]
	v_pk_mul_f32 v[210:211], v[210:211], s[48:49] op_sel_hi:[1,0]
	v_pk_fma_f32 v[16:17], v[16:17], s[50:51], v[208:209] op_sel_hi:[1,0,1]
	v_pk_fma_f32 v[18:19], v[18:19], s[50:51], v[210:211] op_sel_hi:[1,0,1]
	global_store_dwordx4 v245, v[28:31], s[44:45] sc1
	global_store_dwordx4 v245, v[24:27], s[44:45] offset:64 sc1
	global_store_dwordx4 v245, v[20:23], s[44:45] offset:512 sc1
	global_store_dwordx4 v245, v[16:19], s[44:45] offset:576 sc1
	v_add_u32_e32 v245, 0x10000, v245
	s_waitcnt vmcnt(8)
; __device__ __forceinline__ int mk_tid(int wv) { return (wv << 6) | lane_now(); }
; #define PG8_BAR __builtin_amdgcn_s_barrier()
;     __device__ __forceinline__ void operator()(const f32x4 (&acc)[2][2][4][2], const Unit& u, int wr, int wc, int fr, int fq) const {
;     ...
;             for (int m = 0; m < 4; ++m) { const int row = row0 + ai * HALF + m * 16; const size_t ro = (size_t)row * 1024 + col0; const f32x2v st = *(const f32x2v*)(p.stats + 2 * row);
; #pragma unroll
;                 for (int bj = 0; bj < 2; ++bj)
; #pragma unroll
;                     for (int n = 0; n < 2; ++n) { const int c = col0 + bj * HALF + n * 16; const size_t off = ro + bj * HALF + n * 16;
;                         const f32x4 sv = *(const f32x4*)(p.src + off), gv = *(const f32x4*)(p.g + c), bv = *(const f32x4*)(p.b + c);
;                         const f32x4 hv = (sv - st.x) * st.y * gv + bv; *(f32x4*)(z + off) = hv * alpha + acc[ai][bj][m][n] * sc; }
;                 asm volatile("" ::: "memory"); }
; template <class Epi, class Sched, bool ALIGN_EPI = false, bool SP2 = false, bool F8 = false>
; __device__ __forceinline__ void gemm_phase(PG8_LAS unsigned char* lds, const Gemm g, const Sched& S, const Epi& E, const int wv) {
;     ...
;         if constexpr (ALIGN_EPI) { if (wr == 0) PG8_BAR; }
;         if constexpr (!Epi::AFTER_DRAIN) { const int t2_ = ::mk_tid(wv); const int l2_ = t2_ & 63;
;             E(acc, cur, wr, wc, l2_ & 15, l2_ >> 4); S.done(cur); }
;         if (!has_next) break;
; #pragma unroll
;         for (int a = 0; a < 2; ++a)
; #pragma unroll
;             for (int b = 0; b < 2; ++b)
; #pragma unroll
;                 for (int m = 0; m < 4; ++m)
; #pragma unroll
;                     for (int n = 0; n < 2; ++n) acc[a][b][m][n] = (f32x4){0.f, 0.f, 0.f, 0.f};
;         cur = nxt; cA = nA; cB = nB; ++ui;
;         if constexpr (ALIGN_EPI) { if (wr == 1) PG8_BAR; }
	v_sub_f32_e32 v213, v213, v194
	v_sub_f32_e32 v212, v212, v194
	v_sub_f32_e32 v215, v215, v194
	v_sub_f32_e32 v214, v214, v194
	v_pk_mul_f32 v[214:215], v[194:195], v[214:215] op_sel:[1,0]
	v_pk_mul_f32 v[212:213], v[194:195], v[212:213] op_sel:[1,0]
	v_pk_fma_f32 v[214:215], v[150:151], v[214:215], v[166:167]
	v_pk_fma_f32 v[212:213], v[148:149], v[212:213], v[164:165]
	v_pk_mul_f32 v[212:213], v[212:213], s[48:49] op_sel_hi:[1,0]
	v_pk_mul_f32 v[214:215], v[214:215], s[48:49] op_sel_hi:[1,0]
	v_pk_fma_f32 v[12:13], v[12:13], s[50:51], v[212:213] op_sel_hi:[1,0,1]
	v_pk_fma_f32 v[14:15], v[14:15], s[50:51], v[214:215] op_sel_hi:[1,0,1]
	v_sub_f32_e32 v217, v217, v194
	v_sub_f32_e32 v216, v216, v194
	v_sub_f32_e32 v219, v219, v194
	v_sub_f32_e32 v218, v218, v194
	v_pk_mul_f32 v[218:219], v[194:195], v[218:219] op_sel:[1,0]
	v_pk_mul_f32 v[216:217], v[194:195], v[216:217] op_sel:[1,0]
	v_pk_fma_f32 v[218:219], v[154:155], v[218:219], v[170:171]
	v_pk_fma_f32 v[216:217], v[152:153], v[216:217], v[168:169]
	v_pk_mul_f32 v[216:217], v[216:217], s[48:49] op_sel_hi:[1,0]
	v_pk_mul_f32 v[218:219], v[218:219], s[48:49] op_sel_hi:[1,0]
	v_pk_fma_f32 v[8:9], v[8:9], s[50:51], v[216:217] op_sel_hi:[1,0,1]
	v_pk_fma_f32 v[10:11], v[10:11], s[50:51], v[218:219] op_sel_hi:[1,0,1]
	v_sub_f32_e32 v221, v221, v194
	v_sub_f32_e32 v220, v220, v194
	v_sub_f32_e32 v223, v223, v194
	v_sub_f32_e32 v222, v222, v194
	v_pk_mul_f32 v[222:223], v[194:195], v[222:223] op_sel:[1,0]
	v_pk_mul_f32 v[220:221], v[194:195], v[220:221] op_sel:[1,0]
	v_pk_fma_f32 v[222:223], v[158:159], v[222:223], v[174:175]
	v_pk_fma_f32 v[220:221], v[156:157], v[220:221], v[172:173]
	v_pk_mul_f32 v[220:221], v[220:221], s[48:49] op_sel_hi:[1,0]
	v_pk_mul_f32 v[222:223], v[222:223], s[48:49] op_sel_hi:[1,0]
	v_pk_fma_f32 v[4:5], v[4:5], s[50:51], v[220:221] op_sel_hi:[1,0,1]
	v_pk_fma_f32 v[6:7], v[6:7], s[50:51], v[222:223] op_sel_hi:[1,0,1]
	v_sub_f32_e32 v225, v225, v194
	v_sub_f32_e32 v224, v224, v194
	v_sub_f32_e32 v227, v227, v194
	v_sub_f32_e32 v226, v226, v194
	v_pk_mul_f32 v[226:227], v[194:195], v[226:227] op_sel:[1,0]
	v_pk_mul_f32 v[224:225], v[194:195], v[224:225] op_sel:[1,0]
	v_pk_fma_f32 v[226:227], v[162:163], v[226:227], v[178:179]
	v_pk_fma_f32 v[224:225], v[160:161], v[224:225], v[176:177]
	v_pk_mul_f32 v[224:225], v[224:225], s[48:49] op_sel_hi:[1,0]
	v_pk_mul_f32 v[226:227], v[226:227], s[48:49] op_sel_hi:[1,0]
	v_pk_fma_f32 v[0:1], v[0:1], s[50:51], v[224:225] op_sel_hi:[1,0,1]
	v_pk_fma_f32 v[2:3], v[2:3], s[50:51], v[226:227] op_sel_hi:[1,0,1]
	global_store_dwordx4 v245, v[12:15], s[44:45] sc1
	global_store_dwordx4 v245, v[8:11], s[44:45] offset:64 sc1
	global_store_dwordx4 v245, v[4:7], s[44:45] offset:512 sc1
	global_store_dwordx4 v245, v[0:3], s[44:45] offset:576 sc1
	s_cbranch_vccnz .LBB0_972
	s_andn2_b64 vcc, exec, s[24:25]
	s_cbranch_vccnz .LBB0_971
	s_barrier
	s_branch .LBB0_971

;     __device__ __forceinline__ void operator()(const f32x4 (&acc)[2][2][4][2], const Unit& u, int wr, int wc, int fr, int fq) const {
;         int row0 = u.pm * BM + wr * 64 + fr, col0 = u.pn * BM + wc * 32 + 4 * fq; asm volatile("" : "+v"(row0), "+v"(col0));
;         typedef float f32x2v __attribute__((ext_vector_type(2)));
; #pragma unroll
;         for (int ai = 0; ai < 2; ++ai)
; #pragma unroll
;             for (int m = 0; m < 4; ++m) { const int row = row0 + ai * HALF + m * 16; const size_t ro = (size_t)row * 1024 + col0; const f32x2v st = *(const f32x2v*)(p.stats + 2 * row);
; #pragma unroll
;                 for (int bj = 0; bj < 2; ++bj)
; #pragma unroll
;                     for (int n = 0; n < 2; ++n) { const int c = col0 + bj * HALF + n * 16; const size_t off = ro + bj * HALF + n * 16;
;                         const f32x4 sv = *(const f32x4*)(p.src + off), gv = *(const f32x4*)(p.g + c), bv = *(const f32x4*)(p.b + c);
;                         const f32x4 hv = (sv - st.x) * st.y * gv + bv; *(f32x4*)(z + off) = hv * alpha + acc[ai][bj][m][n] * sc; }
;                 asm volatile("" ::: "memory"); }
.LBB0_1822:
	s_lshl_b32 s18, s62, 8
	v_mbcnt_lo_u32_b32 v132, -1, 0
	v_mbcnt_hi_u32_b32 v132, -1, v132
	s_add_i32 s18, s18, s71
	v_and_or_b32 v138, v132, 15, s18
	s_lshl_b32 s18, s61, 8
	v_lshrrev_b32_e32 v132, 2, v132
	v_and_or_b32 v132, v132, 12, s18
	v_or_b32_e32 v136, s75, v132
	s_andn2_b64 vcc, exec, s[8:9]
	v_lshlrev_b32_e32 v244, 12, v138
	v_lshlrev_b32_e32 v246, 3, v138
	v_lshlrev_b32_e32 v247, 2, v136
	v_lshl_add_u32 v244, v136, 2, v244
	global_load_dwordx2 v[180:181], v246, s[26:27]
	global_load_dwordx2 v[182:183], v246, s[26:27] offset:128
	global_load_dwordx2 v[184:185], v246, s[26:27] offset:256
	global_load_dwordx2 v[186:187], v246, s[26:27] offset:384
	global_load_dwordx2 v[188:189], v246, s[26:27] offset:1024
	global_load_dwordx2 v[190:191], v246, s[26:27] offset:1152
	global_load_dwordx2 v[192:193], v246, s[26:27] offset:1280
	global_load_dwordx2 v[194:195], v246, s[26:27] offset:1408
	v_mov_b32_e32 v245, v244
	global_load_dwordx4 v[148:151], v247, s[10:11]
	global_load_dwordx4 v[152:155], v247, s[10:11] offset:64
	global_load_dwordx4 v[156:159], v247, s[10:11] offset:512
	global_load_dwordx4 v[160:163], v247, s[10:11] offset:576
	global_load_dwordx4 v[164:167], v247, s[20:21]
	global_load_dwordx4 v[168:171], v247, s[20:21] offset:64
	global_load_dwordx4 v[172:175], v247, s[20:21] offset:512
	global_load_dwordx4 v[176:179], v247, s[20:21] offset:576
	s_mov_b64 s[8:9], -1
	global_load_dwordx4 v[196:199], v244, s[24:25]
	global_load_dwordx4 v[200:203], v244, s[24:25] offset:64
	global_load_dwordx4 v[204:207], v244, s[24:25] offset:512
	global_load_dwordx4 v[208:211], v244, s[24:25] offset:576
	v_add_u32_e32 v244, 0x10000, v244
	global_load_dwordx4 v[212:215], v244, s[24:25]
	global_load_dwordx4 v[216:219], v244, s[24:25] offset:64
	global_load_dwordx4 v[220:223], v244, s[24:25] offset:512
	global_load_dwordx4 v[224:227], v244, s[24:25] offset:576
	v_add_u32_e32 v244, 0x10000, v244
	global_load_dwordx4 v[228:231], v244, s[24:25]
	global_load_dwordx4 v[232:235], v244, s[24:25] offset:64
	global_load_dwordx4 v[236:239], v244, s[24:25] offset:512
	global_load_dwordx4 v[240:243], v244, s[24:25] offset:576
	v_add_u32_e32 v244, 0x10000, v244
	s_waitcnt vmcnt(8)
	v_sub_f32_e32 v197, v197, v180
	v_sub_f32_e32 v196, v196, v180
	v_sub_f32_e32 v199, v199, v180
	v_sub_f32_e32 v198, v198, v180
	v_pk_mul_f32 v[198:199], v[180:181], v[198:199] op_sel:[1,0]
	v_pk_mul_f32 v[196:197], v[180:181], v[196:197] op_sel:[1,0]
	v_pk_fma_f32 v[198:199], v[150:151], v[198:199], v[166:167]
	v_pk_fma_f32 v[196:197], v[148:149], v[196:197], v[164:165]
	v_pk_fma_f32 v[126:127], v[198:199], s[40:41], v[126:127] op_sel_hi:[1,0,1]
	v_pk_fma_f32 v[124:125], v[196:197], s[40:41], v[124:125] op_sel_hi:[1,0,1]
	v_sub_f32_e32 v201, v201, v180
	v_sub_f32_e32 v200, v200, v180
	v_sub_f32_e32 v203, v203, v180
	v_sub_f32_e32 v202, v202, v180
	v_pk_mul_f32 v[202:203], v[180:181], v[202:203] op_sel:[1,0]
	v_pk_mul_f32 v[200:201], v[180:181], v[200:201] op_sel:[1,0]
	v_pk_fma_f32 v[202:203], v[154:155], v[202:203], v[170:171]
	v_pk_fma_f32 v[200:201], v[152:153], v[200:201], v[168:169]
	v_pk_fma_f32 v[122:123], v[202:203], s[40:41], v[122:123] op_sel_hi:[1,0,1]
	v_pk_fma_f32 v[120:121], v[200:201], s[40:41], v[120:121] op_sel_hi:[1,0,1]
	v_sub_f32_e32 v205, v205, v180
	v_sub_f32_e32 v204, v204, v180
	v_sub_f32_e32 v207, v207, v180
	v_sub_f32_e32 v206, v206, v180
	v_pk_mul_f32 v[206:207], v[180:181], v[206:207] op_sel:[1,0]
	v_pk_mul_f32 v[204:205], v[180:181], v[204:205] op_sel:[1,0]
	v_pk_fma_f32 v[206:207], v[158:159], v[206:207], v[174:175]
	v_pk_fma_f32 v[204:205], v[156:157], v[204:205], v[172:173]
	v_pk_fma_f32 v[118:119], v[206:207], s[40:41], v[118:119] op_sel_hi:[1,0,1]
	v_pk_fma_f32 v[116:117], v[204:205], s[40:41], v[116:117] op_sel_hi:[1,0,1]
	v_sub_f32_e32 v209, v209, v180
	v_sub_f32_e32 v208, v208, v180
	v_sub_f32_e32 v211, v211, v180
	v_sub_f32_e32 v210, v210, v180
	v_pk_mul_f32 v[210:211], v[180:181], v[210:211] op_sel:[1,0]
	v_pk_mul_f32 v[208:209], v[180:181], v[208:209] op_sel:[1,0]
	v_pk_fma_f32 v[210:211], v[162:163], v[210:211], v[178:179]
	v_pk_fma_f32 v[208:209], v[160:161], v[208:209], v[176:177]
	v_pk_fma_f32 v[114:115], v[210:211], s[40:41], v[114:115] op_sel_hi:[1,0,1]
	v_pk_fma_f32 v[112:113], v[208:209], s[40:41], v[112:113] op_sel_hi:[1,0,1]
	global_store_dwordx4 v245, v[124:127], s[28:29] sc1
	global_store_dwordx4 v245, v[120:123], s[28:29] offset:64 sc1
	global_store_dwordx4 v245, v[116:119], s[28:29] offset:512 sc1
	global_store_dwordx4 v245, v[112:115], s[28:29] offset:576 sc1
	v_add_u32_e32 v245, 0x10000, v245
	global_load_dwordx4 v[196:199], v244, s[24:25]
	global_load_dwordx4 v[200:203], v244, s[24:25] offset:64
	global_load_dwordx4 v[204:207], v244, s[24:25] offset:512
	global_load_dwordx4 v[208:211], v244, s[24:25] offset:576
	v_add_u32_e32 v244, 0x50000, v244
	s_waitcnt vmcnt(12)
;     __device__ __forceinline__ void operator()(const f32x4 (&acc)[2][2][4][2], const Unit& u, int wr, int wc, int fr, int fq) const {
;     ...
;             for (int m = 0; m < 4; ++m) { const int row = row0 + ai * HALF + m * 16; const size_t ro = (size_t)row * 1024 + col0; const f32x2v st = *(const f32x2v*)(p.stats + 2 * row);
; #pragma unroll
;                 for (int bj = 0; bj < 2; ++bj)
; #pragma unroll
;                     for (int n = 0; n < 2; ++n) { const int c = col0 + bj * HALF + n * 16; const size_t off = ro + bj * HALF + n * 16;
;                         const f32x4 sv = *(const f32x4*)(p.src + off), gv = *(const f32x4*)(p.g + c), bv = *(const f32x4*)(p.b + c);
;                         const f32x4 hv = (sv - st.x) * st.y * gv + bv; *(f32x4*)(z + off) = hv * alpha + acc[ai][bj][m][n] * sc; }
;                 asm volatile("" ::: "memory"); }
	v_sub_f32_e32 v213, v213, v182
	v_sub_f32_e32 v212, v212, v182
	v_sub_f32_e32 v215, v215, v182
	v_sub_f32_e32 v214, v214, v182
	v_pk_mul_f32 v[214:215], v[182:183], v[214:215] op_sel:[1,0]
	v_pk_mul_f32 v[212:213], v[182:183], v[212:213] op_sel:[1,0]
	v_pk_fma_f32 v[214:215], v[150:151], v[214:215], v[166:167]
	v_pk_fma_f32 v[212:213], v[148:149], v[212:213], v[164:165]
	v_pk_fma_f32 v[110:111], v[214:215], s[40:41], v[110:111] op_sel_hi:[1,0,1]
	v_pk_fma_f32 v[108:109], v[212:213], s[40:41], v[108:109] op_sel_hi:[1,0,1]
	v_sub_f32_e32 v217, v217, v182
	v_sub_f32_e32 v216, v216, v182
	v_sub_f32_e32 v219, v219, v182
	v_sub_f32_e32 v218, v218, v182
	v_pk_mul_f32 v[218:219], v[182:183], v[218:219] op_sel:[1,0]
	v_pk_mul_f32 v[216:217], v[182:183], v[216:217] op_sel:[1,0]
	v_pk_fma_f32 v[218:219], v[154:155], v[218:219], v[170:171]
	v_pk_fma_f32 v[216:217], v[152:153], v[216:217], v[168:169]
	v_pk_fma_f32 v[106:107], v[218:219], s[40:41], v[106:107] op_sel_hi:[1,0,1]
	v_pk_fma_f32 v[104:105], v[216:217], s[40:41], v[104:105] op_sel_hi:[1,0,1]
	v_sub_f32_e32 v221, v221, v182
	v_sub_f32_e32 v220, v220, v182
	v_sub_f32_e32 v223, v223, v182
	v_sub_f32_e32 v222, v222, v182
	v_pk_mul_f32 v[222:223], v[182:183], v[222:223] op_sel:[1,0]
	v_pk_mul_f32 v[220:221], v[182:183], v[220:221] op_sel:[1,0]
	v_pk_fma_f32 v[222:223], v[158:159], v[222:223], v[174:175]
	v_pk_fma_f32 v[220:221], v[156:157], v[220:221], v[172:173]
	v_pk_fma_f32 v[102:103], v[222:223], s[40:41], v[102:103] op_sel_hi:[1,0,1]
	v_pk_fma_f32 v[100:101], v[220:221], s[40:41], v[100:101] op_sel_hi:[1,0,1]
	v_sub_f32_e32 v225, v225, v182
	v_sub_f32_e32 v224, v224, v182
	v_sub_f32_e32 v227, v227, v182
	v_sub_f32_e32 v226, v226, v182
	v_pk_mul_f32 v[226:227], v[182:183], v[226:227] op_sel:[1,0]
	v_pk_mul_f32 v[224:225], v[182:183], v[224:225] op_sel:[1,0]
	v_pk_fma_f32 v[226:227], v[162:163], v[226:227], v[178:179]
	v_pk_fma_f32 v[224:225], v[160:161], v[224:225], v[176:177]
	v_pk_fma_f32 v[98:99], v[226:227], s[40:41], v[98:99] op_sel_hi:[1,0,1]
	v_pk_fma_f32 v[96:97], v[224:225], s[40:41], v[96:97] op_sel_hi:[1,0,1]
	global_store_dwordx4 v245, v[108:111], s[28:29] sc1
	global_store_dwordx4 v245, v[104:107], s[28:29] offset:64 sc1
	global_store_dwordx4 v245, v[100:103], s[28:29] offset:512 sc1
	global_store_dwordx4 v245, v[96:99], s[28:29] offset:576 sc1
	v_add_u32_e32 v245, 0x10000, v245
	global_load_dwordx4 v[212:215], v244, s[24:25]
	global_load_dwordx4 v[216:219], v244, s[24:25] offset:64
	global_load_dwordx4 v[220:223], v244, s[24:25] offset:512
	global_load_dwordx4 v[224:227], v244, s[24:25] offset:576
	v_add_u32_e32 v244, 0x10000, v244
	s_waitcnt vmcnt(16)
	v_sub_f32_e32 v229, v229, v184
	v_sub_f32_e32 v228, v228, v184
	v_sub_f32_e32 v231, v231, v184
	v_sub_f32_e32 v230, v230, v184
	v_pk_mul_f32 v[230:231], v[184:185], v[230:231] op_sel:[1,0]
	v_pk_mul_f32 v[228:229], v[184:185], v[228:229] op_sel:[1,0]
	v_pk_fma_f32 v[230:231], v[150:151], v[230:231], v[166:167]
	v_pk_fma_f32 v[228:229], v[148:149], v[228:229], v[164:165]
	v_pk_fma_f32 v[94:95], v[230:231], s[40:41], v[94:95] op_sel_hi:[1,0,1]
	v_pk_fma_f32 v[92:93], v[228:229], s[40:41], v[92:93] op_sel_hi:[1,0,1]
	v_sub_f32_e32 v233, v233, v184
	v_sub_f32_e32 v232, v232, v184
	v_sub_f32_e32 v235, v235, v184
	v_sub_f32_e32 v234, v234, v184
	v_pk_mul_f32 v[234:235], v[184:185], v[234:235] op_sel:[1,0]
	v_pk_mul_f32 v[232:233], v[184:185], v[232:233] op_sel:[1,0]
	v_pk_fma_f32 v[234:235], v[154:155], v[234:235], v[170:171]
	v_pk_fma_f32 v[232:233], v[152:153], v[232:233], v[168:169]
	v_pk_fma_f32 v[90:91], v[234:235], s[40:41], v[90:91] op_sel_hi:[1,0,1]
	v_pk_fma_f32 v[88:89], v[232:233], s[40:41], v[88:89] op_sel_hi:[1,0,1]
	v_sub_f32_e32 v237, v237, v184
	v_sub_f32_e32 v236, v236, v184
	v_sub_f32_e32 v239, v239, v184
	v_sub_f32_e32 v238, v238, v184
	v_pk_mul_f32 v[238:239], v[184:185], v[238:239] op_sel:[1,0]
	v_pk_mul_f32 v[236:237], v[184:185], v[236:237] op_sel:[1,0]
	v_pk_fma_f32 v[238:239], v[158:159], v[238:239], v[174:175]
	v_pk_fma_f32 v[236:237], v[156:157], v[236:237], v[172:173]
	v_pk_fma_f32 v[86:87], v[238:239], s[40:41], v[86:87] op_sel_hi:[1,0,1]
	v_pk_fma_f32 v[84:85], v[236:237], s[40:41], v[84:85] op_sel_hi:[1,0,1]
	v_sub_f32_e32 v241, v241, v184
	v_sub_f32_e32 v240, v240, v184
	v_sub_f32_e32 v243, v243, v184
	v_sub_f32_e32 v242, v242, v184
	v_pk_mul_f32 v[242:243], v[184:185], v[242:243] op_sel:[1,0]
	v_pk_mul_f32 v[240:241], v[184:185], v[240:241] op_sel:[1,0]
	v_pk_fma_f32 v[242:243], v[162:163], v[242:243], v[178:179]
	v_pk_fma_f32 v[240:241], v[160:161], v[240:241], v[176:177]
	v_pk_fma_f32 v[82:83], v[242:243], s[40:41], v[82:83] op_sel_hi:[1,0,1]
	v_pk_fma_f32 v[80:81], v[240:241], s[40:41], v[80:81] op_sel_hi:[1,0,1]
	global_store_dwordx4 v245, v[92:95], s[28:29] sc1
	global_store_dwordx4 v245, v[88:91], s[28:29] offset:64 sc1
	global_store_dwordx4 v245, v[84:87], s[28:29] offset:512 sc1
	global_store_dwordx4 v245, v[80:83], s[28:29] offset:576 sc1
	v_add_u32_e32 v245, 0x10000, v245
	global_load_dwordx4 v[228:231], v244, s[24:25]
	global_load_dwordx4 v[232:235], v244, s[24:25] offset:64
	global_load_dwordx4 v[236:239], v244, s[24:25] offset:512
	global_load_dwordx4 v[240:243], v244, s[24:25] offset:576
	v_add_u32_e32 v244, 0x10000, v244
	s_waitcnt vmcnt(16)
;     __device__ __forceinline__ void operator()(const f32x4 (&acc)[2][2][4][2], const Unit& u, int wr, int wc, int fr, int fq) const {
;     ...
;             for (int m = 0; m < 4; ++m) { const int row = row0 + ai * HALF + m * 16; const size_t ro = (size_t)row * 1024 + col0; const f32x2v st = *(const f32x2v*)(p.stats + 2 * row);
; #pragma unroll
;                 for (int bj = 0; bj < 2; ++bj)
; #pragma unroll
;                     for (int n = 0; n < 2; ++n) { const int c = col0 + bj * HALF + n * 16; const size_t off = ro + bj * HALF + n * 16;
;                         const f32x4 sv = *(const f32x4*)(p.src + off), gv = *(const f32x4*)(p.g + c), bv = *(const f32x4*)(p.b + c);
;                         const f32x4 hv = (sv - st.x) * st.y * gv + bv; *(f32x4*)(z + off) = hv * alpha + acc[ai][bj][m][n] * sc; }
;                 asm volatile("" ::: "memory"); }
	v_sub_f32_e32 v197, v197, v186
	v_sub_f32_e32 v196, v196, v186
	v_sub_f32_e32 v199, v199, v186
	v_sub_f32_e32 v198, v198, v186
	v_pk_mul_f32 v[198:199], v[186:187], v[198:199] op_sel:[1,0]
	v_pk_mul_f32 v[196:197], v[186:187], v[196:197] op_sel:[1,0]
	v_pk_fma_f32 v[198:199], v[150:151], v[198:199], v[166:167]
	v_pk_fma_f32 v[196:197], v[148:149], v[196:197], v[164:165]
	v_pk_fma_f32 v[78:79], v[198:199], s[40:41], v[78:79] op_sel_hi:[1,0,1]
	v_pk_fma_f32 v[76:77], v[196:197], s[40:41], v[76:77] op_sel_hi:[1,0,1]
	v_sub_f32_e32 v201, v201, v186
	v_sub_f32_e32 v200, v200, v186
	v_sub_f32_e32 v203, v203, v186
	v_sub_f32_e32 v202, v202, v186
	v_pk_mul_f32 v[202:203], v[186:187], v[202:203] op_sel:[1,0]
	v_pk_mul_f32 v[200:201], v[186:187], v[200:201] op_sel:[1,0]
	v_pk_fma_f32 v[202:203], v[154:155], v[202:203], v[170:171]
	v_pk_fma_f32 v[200:201], v[152:153], v[200:201], v[168:169]
	v_pk_fma_f32 v[74:75], v[202:203], s[40:41], v[74:75] op_sel_hi:[1,0,1]
	v_pk_fma_f32 v[72:73], v[200:201], s[40:41], v[72:73] op_sel_hi:[1,0,1]
	v_sub_f32_e32 v205, v205, v186
	v_sub_f32_e32 v204, v204, v186
	v_sub_f32_e32 v207, v207, v186
	v_sub_f32_e32 v206, v206, v186
	v_pk_mul_f32 v[206:207], v[186:187], v[206:207] op_sel:[1,0]
	v_pk_mul_f32 v[204:205], v[186:187], v[204:205] op_sel:[1,0]
	v_pk_fma_f32 v[206:207], v[158:159], v[206:207], v[174:175]
	v_pk_fma_f32 v[204:205], v[156:157], v[204:205], v[172:173]
	v_pk_fma_f32 v[70:71], v[206:207], s[40:41], v[70:71] op_sel_hi:[1,0,1]
	v_pk_fma_f32 v[68:69], v[204:205], s[40:41], v[68:69] op_sel_hi:[1,0,1]
	v_sub_f32_e32 v209, v209, v186
	v_sub_f32_e32 v208, v208, v186
	v_sub_f32_e32 v211, v211, v186
	v_sub_f32_e32 v210, v210, v186
	v_pk_mul_f32 v[210:211], v[186:187], v[210:211] op_sel:[1,0]
	v_pk_mul_f32 v[208:209], v[186:187], v[208:209] op_sel:[1,0]
	v_pk_fma_f32 v[210:211], v[162:163], v[210:211], v[178:179]
	v_pk_fma_f32 v[208:209], v[160:161], v[208:209], v[176:177]
	v_pk_fma_f32 v[66:67], v[210:211], s[40:41], v[66:67] op_sel_hi:[1,0,1]
	v_pk_fma_f32 v[64:65], v[208:209], s[40:41], v[64:65] op_sel_hi:[1,0,1]
	global_store_dwordx4 v245, v[76:79], s[28:29] sc1
	global_store_dwordx4 v245, v[72:75], s[28:29] offset:64 sc1
	global_store_dwordx4 v245, v[68:71], s[28:29] offset:512 sc1
	global_store_dwordx4 v245, v[64:67], s[28:29] offset:576 sc1
	v_add_u32_e32 v245, 0x50000, v245
	global_load_dwordx4 v[196:199], v244, s[24:25]
	global_load_dwordx4 v[200:203], v244, s[24:25] offset:64
	global_load_dwordx4 v[204:207], v244, s[24:25] offset:512
	global_load_dwordx4 v[208:211], v244, s[24:25] offset:576
	v_add_u32_e32 v244, 0x10000, v244
	s_waitcnt vmcnt(16)
	v_sub_f32_e32 v213, v213, v188
	v_sub_f32_e32 v212, v212, v188
	v_sub_f32_e32 v215, v215, v188
	v_sub_f32_e32 v214, v214, v188
	v_pk_mul_f32 v[214:215], v[188:189], v[214:215] op_sel:[1,0]
	v_pk_mul_f32 v[212:213], v[188:189], v[212:213] op_sel:[1,0]
	v_pk_fma_f32 v[214:215], v[150:151], v[214:215], v[166:167]
	v_pk_fma_f32 v[212:213], v[148:149], v[212:213], v[164:165]
	v_pk_fma_f32 v[62:63], v[214:215], s[40:41], v[62:63] op_sel_hi:[1,0,1]
	v_pk_fma_f32 v[60:61], v[212:213], s[40:41], v[60:61] op_sel_hi:[1,0,1]
	v_sub_f32_e32 v217, v217, v188
	v_sub_f32_e32 v216, v216, v188
	v_sub_f32_e32 v219, v219, v188
	v_sub_f32_e32 v218, v218, v188
	v_pk_mul_f32 v[218:219], v[188:189], v[218:219] op_sel:[1,0]
	v_pk_mul_f32 v[216:217], v[188:189], v[216:217] op_sel:[1,0]
	v_pk_fma_f32 v[218:219], v[154:155], v[218:219], v[170:171]
	v_pk_fma_f32 v[216:217], v[152:153], v[216:217], v[168:169]
	v_pk_fma_f32 v[58:59], v[218:219], s[40:41], v[58:59] op_sel_hi:[1,0,1]
	v_pk_fma_f32 v[56:57], v[216:217], s[40:41], v[56:57] op_sel_hi:[1,0,1]
	v_sub_f32_e32 v221, v221, v188
	v_sub_f32_e32 v220, v220, v188
	v_sub_f32_e32 v223, v223, v188
	v_sub_f32_e32 v222, v222, v188
	v_pk_mul_f32 v[222:223], v[188:189], v[222:223] op_sel:[1,0]
	v_pk_mul_f32 v[220:221], v[188:189], v[220:221] op_sel:[1,0]
	v_pk_fma_f32 v[222:223], v[158:159], v[222:223], v[174:175]
	v_pk_fma_f32 v[220:221], v[156:157], v[220:221], v[172:173]
	v_pk_fma_f32 v[54:55], v[222:223], s[40:41], v[54:55] op_sel_hi:[1,0,1]
	v_pk_fma_f32 v[52:53], v[220:221], s[40:41], v[52:53] op_sel_hi:[1,0,1]
	v_sub_f32_e32 v225, v225, v188
	v_sub_f32_e32 v224, v224, v188
	v_sub_f32_e32 v227, v227, v188
	v_sub_f32_e32 v226, v226, v188
	v_pk_mul_f32 v[226:227], v[188:189], v[226:227] op_sel:[1,0]
	v_pk_mul_f32 v[224:225], v[188:189], v[224:225] op_sel:[1,0]
	v_pk_fma_f32 v[226:227], v[162:163], v[226:227], v[178:179]
	v_pk_fma_f32 v[224:225], v[160:161], v[224:225], v[176:177]
	v_pk_fma_f32 v[50:51], v[226:227], s[40:41], v[50:51] op_sel_hi:[1,0,1]
	v_pk_fma_f32 v[48:49], v[224:225], s[40:41], v[48:49] op_sel_hi:[1,0,1]
	global_store_dwordx4 v245, v[60:63], s[28:29] sc1
	global_store_dwordx4 v245, v[56:59], s[28:29] offset:64 sc1
	global_store_dwordx4 v245, v[52:55], s[28:29] offset:512 sc1
	global_store_dwordx4 v245, v[48:51], s[28:29] offset:576 sc1
	v_add_u32_e32 v245, 0x10000, v245
	global_load_dwordx4 v[212:215], v244, s[24:25]
	global_load_dwordx4 v[216:219], v244, s[24:25] offset:64
	global_load_dwordx4 v[220:223], v244, s[24:25] offset:512
	global_load_dwordx4 v[224:227], v244, s[24:25] offset:576
	s_waitcnt vmcnt(16)
;     __device__ __forceinline__ void operator()(const f32x4 (&acc)[2][2][4][2], const Unit& u, int wr, int wc, int fr, int fq) const {
;     ...
;             for (int m = 0; m < 4; ++m) { const int row = row0 + ai * HALF + m * 16; const size_t ro = (size_t)row * 1024 + col0; const f32x2v st = *(const f32x2v*)(p.stats + 2 * row);
; #pragma unroll
;                 for (int bj = 0; bj < 2; ++bj)
; #pragma unroll
;                     for (int n = 0; n < 2; ++n) { const int c = col0 + bj * HALF + n * 16; const size_t off = ro + bj * HALF + n * 16;
;                         const f32x4 sv = *(const f32x4*)(p.src + off), gv = *(const f32x4*)(p.g + c), bv = *(const f32x4*)(p.b + c);
;                         const f32x4 hv = (sv - st.x) * st.y * gv + bv; *(f32x4*)(z + off) = hv * alpha + acc[ai][bj][m][n] * sc; }
;                 asm volatile("" ::: "memory"); }
	v_sub_f32_e32 v229, v229, v190
	v_sub_f32_e32 v228, v228, v190
	v_sub_f32_e32 v231, v231, v190
	v_sub_f32_e32 v230, v230, v190
	v_pk_mul_f32 v[230:231], v[190:191], v[230:231] op_sel:[1,0]
	v_pk_mul_f32 v[228:229], v[190:191], v[228:229] op_sel:[1,0]
	v_pk_fma_f32 v[230:231], v[150:151], v[230:231], v[166:167]
	v_pk_fma_f32 v[228:229], v[148:149], v[228:229], v[164:165]
	v_pk_fma_f32 v[46:47], v[230:231], s[40:41], v[46:47] op_sel_hi:[1,0,1]
	v_pk_fma_f32 v[44:45], v[228:229], s[40:41], v[44:45] op_sel_hi:[1,0,1]
	v_sub_f32_e32 v233, v233, v190
	v_sub_f32_e32 v232, v232, v190
	v_sub_f32_e32 v235, v235, v190
	v_sub_f32_e32 v234, v234, v190
	v_pk_mul_f32 v[234:235], v[190:191], v[234:235] op_sel:[1,0]
	v_pk_mul_f32 v[232:233], v[190:191], v[232:233] op_sel:[1,0]
	v_pk_fma_f32 v[234:235], v[154:155], v[234:235], v[170:171]
	v_pk_fma_f32 v[232:233], v[152:153], v[232:233], v[168:169]
	v_pk_fma_f32 v[42:43], v[234:235], s[40:41], v[42:43] op_sel_hi:[1,0,1]
	v_pk_fma_f32 v[40:41], v[232:233], s[40:41], v[40:41] op_sel_hi:[1,0,1]
	v_sub_f32_e32 v237, v237, v190
	v_sub_f32_e32 v236, v236, v190
	v_sub_f32_e32 v239, v239, v190
	v_sub_f32_e32 v238, v238, v190
	v_pk_mul_f32 v[238:239], v[190:191], v[238:239] op_sel:[1,0]
	v_pk_mul_f32 v[236:237], v[190:191], v[236:237] op_sel:[1,0]
	v_pk_fma_f32 v[238:239], v[158:159], v[238:239], v[174:175]
	v_pk_fma_f32 v[236:237], v[156:157], v[236:237], v[172:173]
	v_pk_fma_f32 v[38:39], v[238:239], s[40:41], v[38:39] op_sel_hi:[1,0,1]
	v_pk_fma_f32 v[36:37], v[236:237], s[40:41], v[36:37] op_sel_hi:[1,0,1]
	v_sub_f32_e32 v241, v241, v190
	v_sub_f32_e32 v240, v240, v190
	v_sub_f32_e32 v243, v243, v190
	v_sub_f32_e32 v242, v242, v190
	v_pk_mul_f32 v[242:243], v[190:191], v[242:243] op_sel:[1,0]
	v_pk_mul_f32 v[240:241], v[190:191], v[240:241] op_sel:[1,0]
	v_pk_fma_f32 v[242:243], v[162:163], v[242:243], v[178:179]
	v_pk_fma_f32 v[240:241], v[160:161], v[240:241], v[176:177]
	v_pk_fma_f32 v[34:35], v[242:243], s[40:41], v[34:35] op_sel_hi:[1,0,1]
	v_pk_fma_f32 v[32:33], v[240:241], s[40:41], v[32:33] op_sel_hi:[1,0,1]
	global_store_dwordx4 v245, v[44:47], s[28:29] sc1
	global_store_dwordx4 v245, v[40:43], s[28:29] offset:64 sc1
	global_store_dwordx4 v245, v[36:39], s[28:29] offset:512 sc1
	global_store_dwordx4 v245, v[32:35], s[28:29] offset:576 sc1
	v_add_u32_e32 v245, 0x10000, v245
	s_waitcnt vmcnt(12)
	v_sub_f32_e32 v197, v197, v192
	v_sub_f32_e32 v196, v196, v192
	v_sub_f32_e32 v199, v199, v192
	v_sub_f32_e32 v198, v198, v192
	v_pk_mul_f32 v[198:199], v[192:193], v[198:199] op_sel:[1,0]
	v_pk_mul_f32 v[196:197], v[192:193], v[196:197] op_sel:[1,0]
	v_pk_fma_f32 v[198:199], v[150:151], v[198:199], v[166:167]
	v_pk_fma_f32 v[196:197], v[148:149], v[196:197], v[164:165]
	v_pk_fma_f32 v[30:31], v[198:199], s[40:41], v[30:31] op_sel_hi:[1,0,1]
	v_pk_fma_f32 v[28:29], v[196:197], s[40:41], v[28:29] op_sel_hi:[1,0,1]
	v_sub_f32_e32 v201, v201, v192
	v_sub_f32_e32 v200, v200, v192
	v_sub_f32_e32 v203, v203, v192
	v_sub_f32_e32 v202, v202, v192
	v_pk_mul_f32 v[202:203], v[192:193], v[202:203] op_sel:[1,0]
	v_pk_mul_f32 v[200:201], v[192:193], v[200:201] op_sel:[1,0]
	v_pk_fma_f32 v[202:203], v[154:155], v[202:203], v[170:171]
	v_pk_fma_f32 v[200:201], v[152:153], v[200:201], v[168:169]
	v_pk_fma_f32 v[26:27], v[202:203], s[40:41], v[26:27] op_sel_hi:[1,0,1]
	v_pk_fma_f32 v[24:25], v[200:201], s[40:41], v[24:25] op_sel_hi:[1,0,1]
	v_sub_f32_e32 v205, v205, v192
	v_sub_f32_e32 v204, v204, v192
	v_sub_f32_e32 v207, v207, v192
	v_sub_f32_e32 v206, v206, v192
	v_pk_mul_f32 v[206:207], v[192:193], v[206:207] op_sel:[1,0]
	v_pk_mul_f32 v[204:205], v[192:193], v[204:205] op_sel:[1,0]
	v_pk_fma_f32 v[206:207], v[158:159], v[206:207], v[174:175]
	v_pk_fma_f32 v[204:205], v[156:157], v[204:205], v[172:173]
	v_pk_fma_f32 v[22:23], v[206:207], s[40:41], v[22:23] op_sel_hi:[1,0,1]
	v_pk_fma_f32 v[20:21], v[204:205], s[40:41], v[20:21] op_sel_hi:[1,0,1]
	v_sub_f32_e32 v209, v209, v192
	v_sub_f32_e32 v208, v208, v192
	v_sub_f32_e32 v211, v211, v192
	v_sub_f32_e32 v210, v210, v192
	v_pk_mul_f32 v[210:211], v[192:193], v[210:211] op_sel:[1,0]
	v_pk_mul_f32 v[208:209], v[192:193], v[208:209] op_sel:[1,0]
	v_pk_fma_f32 v[210:211], v[162:163], v[210:211], v[178:179]
	v_pk_fma_f32 v[208:209], v[160:161], v[208:209], v[176:177]
	v_pk_fma_f32 v[18:19], v[210:211], s[40:41], v[18:19] op_sel_hi:[1,0,1]
	v_pk_fma_f32 v[16:17], v[208:209], s[40:41], v[16:17] op_sel_hi:[1,0,1]
	global_store_dwordx4 v245, v[28:31], s[28:29] sc1
	global_store_dwordx4 v245, v[24:27], s[28:29] offset:64 sc1
	global_store_dwordx4 v245, v[20:23], s[28:29] offset:512 sc1
	global_store_dwordx4 v245, v[16:19], s[28:29] offset:576 sc1
	v_add_u32_e32 v245, 0x10000, v245
	s_waitcnt vmcnt(8)
; __device__ __forceinline__ int mk_tid(int wv) { return (wv << 6) | lane_now(); }
; #define PG8_BAR __builtin_amdgcn_s_barrier()
;     __device__ __forceinline__ void operator()(const f32x4 (&acc)[2][2][4][2], const Unit& u, int wr, int wc, int fr, int fq) const {
;     ...
;             for (int m = 0; m < 4; ++m) { const int row = row0 + ai * HALF + m * 16; const size_t ro = (size_t)row * 1024 + col0; const f32x2v st = *(const f32x2v*)(p.stats + 2 * row);
; #pragma unroll
;                 for (int bj = 0; bj < 2; ++bj)
; #pragma unroll
;                     for (int n = 0; n < 2; ++n) { const int c = col0 + bj * HALF + n * 16; const size_t off = ro + bj * HALF + n * 16;
;                         const f32x4 sv = *(const f32x4*)(p.src + off), gv = *(const f32x4*)(p.g + c), bv = *(const f32x4*)(p.b + c);
;                         const f32x4 hv = (sv - st.x) * st.y * gv + bv; *(f32x4*)(z + off) = hv * alpha + acc[ai][bj][m][n] * sc; }
;                 asm volatile("" ::: "memory"); }
; template <class Epi, class Sched, bool ALIGN_EPI = false, bool SP2 = false, bool F8 = false>
; __device__ __forceinline__ void gemm_phase(PG8_LAS unsigned char* lds, const Gemm g, const Sched& S, const Epi& E, const int wv) {
;     ...
;         if constexpr (ALIGN_EPI) { if (wr == 0) PG8_BAR; }
;         if constexpr (!Epi::AFTER_DRAIN) { const int t2_ = ::mk_tid(wv); const int l2_ = t2_ & 63;
;             E(acc, cur, wr, wc, l2_ & 15, l2_ >> 4); S.done(cur); }
;         if (!has_next) break;
; #pragma unroll
;         for (int a = 0; a < 2; ++a)
; #pragma unroll
;             for (int b = 0; b < 2; ++b)
; #pragma unroll
;                 for (int m = 0; m < 4; ++m)
; #pragma unroll
;                     for (int n = 0; n < 2; ++n) acc[a][b][m][n] = (f32x4){0.f, 0.f, 0.f, 0.f};
;         cur = nxt; cA = nA; cB = nB; ++ui;
;         if constexpr (ALIGN_EPI) { if (wr == 1) PG8_BAR; }
	v_sub_f32_e32 v213, v213, v194
	v_sub_f32_e32 v212, v212, v194
	v_sub_f32_e32 v215, v215, v194
	v_sub_f32_e32 v214, v214, v194
	v_pk_mul_f32 v[214:215], v[194:195], v[214:215] op_sel:[1,0]
	v_pk_mul_f32 v[212:213], v[194:195], v[212:213] op_sel:[1,0]
	v_pk_fma_f32 v[214:215], v[150:151], v[214:215], v[166:167]
	v_pk_fma_f32 v[212:213], v[148:149], v[212:213], v[164:165]
	v_pk_fma_f32 v[14:15], v[214:215], s[40:41], v[14:15] op_sel_hi:[1,0,1]
	v_pk_fma_f32 v[12:13], v[212:213], s[40:41], v[12:13] op_sel_hi:[1,0,1]
	v_sub_f32_e32 v217, v217, v194
	v_sub_f32_e32 v216, v216, v194
	v_sub_f32_e32 v219, v219, v194
	v_sub_f32_e32 v218, v218, v194
	v_pk_mul_f32 v[218:219], v[194:195], v[218:219] op_sel:[1,0]
	v_pk_mul_f32 v[216:217], v[194:195], v[216:217] op_sel:[1,0]
	v_pk_fma_f32 v[218:219], v[154:155], v[218:219], v[170:171]
	v_pk_fma_f32 v[216:217], v[152:153], v[216:217], v[168:169]
	v_pk_fma_f32 v[10:11], v[218:219], s[40:41], v[10:11] op_sel_hi:[1,0,1]
	v_pk_fma_f32 v[8:9], v[216:217], s[40:41], v[8:9] op_sel_hi:[1,0,1]
	v_sub_f32_e32 v221, v221, v194
	v_sub_f32_e32 v220, v220, v194
	v_sub_f32_e32 v223, v223, v194
	v_sub_f32_e32 v222, v222, v194
	v_pk_mul_f32 v[222:223], v[194:195], v[222:223] op_sel:[1,0]
	v_pk_mul_f32 v[220:221], v[194:195], v[220:221] op_sel:[1,0]
	v_pk_fma_f32 v[222:223], v[158:159], v[222:223], v[174:175]
	v_pk_fma_f32 v[220:221], v[156:157], v[220:221], v[172:173]
	v_pk_fma_f32 v[6:7], v[222:223], s[40:41], v[6:7] op_sel_hi:[1,0,1]
	v_pk_fma_f32 v[4:5], v[220:221], s[40:41], v[4:5] op_sel_hi:[1,0,1]
	v_sub_f32_e32 v225, v225, v194
	v_sub_f32_e32 v224, v224, v194
	v_sub_f32_e32 v227, v227, v194
	v_sub_f32_e32 v226, v226, v194
	v_pk_mul_f32 v[226:227], v[194:195], v[226:227] op_sel:[1,0]
	v_pk_mul_f32 v[224:225], v[194:195], v[224:225] op_sel:[1,0]
	v_pk_fma_f32 v[226:227], v[162:163], v[226:227], v[178:179]
	v_pk_fma_f32 v[224:225], v[160:161], v[224:225], v[176:177]
	v_pk_fma_f32 v[2:3], v[226:227], s[40:41], v[2:3] op_sel_hi:[1,0,1]
	v_pk_fma_f32 v[0:1], v[224:225], s[40:41], v[0:1] op_sel_hi:[1,0,1]
	global_store_dwordx4 v245, v[12:15], s[28:29] sc1
	global_store_dwordx4 v245, v[8:11], s[28:29] offset:64 sc1
	global_store_dwordx4 v245, v[4:7], s[28:29] offset:512 sc1
	global_store_dwordx4 v245, v[0:3], s[28:29] offset:576 sc1
	s_cbranch_vccnz .LBB0_1811
	s_andn2_b64 vcc, exec, s[22:23]
	s_cbranch_vccnz .LBB0_1810
	s_barrier
	s_branch .LBB0_1810
